# xcd barrier after phase 0; ctx-row split-K partial sums batched; scan loops consume prefetch at iteration end without waiting for store acks
# speedup vs baseline: 1.0137x; 1.0137x over previous
; __device__ __forceinline__ f32x4 ld_bf4(const bf16* p) { const u32x2 w = *(const u32x2*)p; return (f32x4){__builtin_bit_cast(float, w.x << 16), __builtin_bit_cast(float, w.x & 0xffff0000u), __builtin_bit_cast(float, w.y << 16), __builtin_bit_cast(float, w.y & 0xffff0000u)}; }
; __device__ __forceinline__ void rowwise_phase(const Params& P, int mrows, bool first, int l_post, int j_post, int gate_idx, float coef, bool final_, int l_pre, int j_pre, int shift_idx, int scale_idx) {
;     ...
;             if (row < MLAT) {
;                 const bf16* yb = (const bf16*)Y + (size_t)row * DM;
; #pragma unroll
;                 for (int j = 0; j < 8; ++j) { const u32x2 w = *(const u32x2*)(yb + 4 * lane + 256 * j);
;                     yv[j] = (f32x4){__builtin_bit_cast(float, w.x << 16), __builtin_bit_cast(float, w.x & 0xffff0000u), __builtin_bit_cast(float, w.y << 16), __builtin_bit_cast(float, w.y & 0xffff0000u)}; }
;             } else {
;                 const bf16* pr = (const bf16*)(P.ws + WS_YD) + (size_t)(row - MLAT) * DM;
; #pragma unroll
;                 for (int j = 0; j < 8; ++j) yv[j] = ld_bf4(pr + 4 * lane + 256 * j);
;                 for (int ks = 1; ks < 8; ++ks) {
; #pragma unroll
;                     for (int j = 0; j < 8; ++j) yv[j] += ld_bf4(pr + (size_t)ks * MCTX * DM + 4 * lane + 256 * j);
;                 }
.LBB0_21:
	s_cmpk_gt_i32 s4, 0x1fff
	s_mov_b64 s[14:15], -1
	s_cbranch_scc0 .LBB0_23
	s_add_i32 s58, s4, 0xffffe000
	s_lshl_b64 s[14:15], s[58:59], 12
	s_add_u32 s14, s14, s94
	s_addc_u32 s15, s15, s95
	s_add_u32 s14, s14, 0x34f00000
	s_addc_u32 s15, s15, 0
	v_lshlrev_b32_e32 v52, 3, v174
	global_load_dwordx2 v[6:7], v52, s[14:15] offset:0
	global_load_dwordx2 v[10:11], v52, s[14:15] offset:512
	global_load_dwordx2 v[18:19], v52, s[14:15] offset:1024
	global_load_dwordx2 v[14:15], v52, s[14:15] offset:1536
	global_load_dwordx2 v[22:23], v52, s[14:15] offset:2048
	global_load_dwordx2 v[26:27], v52, s[14:15] offset:2560
	global_load_dwordx2 v[30:31], v52, s[14:15] offset:3072
	global_load_dwordx2 v[34:35], v52, s[14:15] offset:3584
	s_add_u32 s14, s14, 0x400000
	s_addc_u32 s15, s15, 0
	global_load_dwordx2 v[36:37], v52, s[14:15] offset:0
	global_load_dwordx2 v[38:39], v52, s[14:15] offset:512
	global_load_dwordx2 v[40:41], v52, s[14:15] offset:1024
	global_load_dwordx2 v[42:43], v52, s[14:15] offset:1536
	global_load_dwordx2 v[44:45], v52, s[14:15] offset:2048
	global_load_dwordx2 v[46:47], v52, s[14:15] offset:2560
	global_load_dwordx2 v[48:49], v52, s[14:15] offset:3072
	global_load_dwordx2 v[50:51], v52, s[14:15] offset:3584
	s_waitcnt vmcnt(15)
	v_lshlrev_b32_e32 v4, 16, v6
	v_and_b32_e32 v5, 0xffff0000, v6
	v_lshlrev_b32_e32 v6, 16, v7
	v_and_b32_e32 v7, 0xffff0000, v7
	s_waitcnt vmcnt(14)
	v_lshlrev_b32_e32 v8, 16, v10
	v_and_b32_e32 v9, 0xffff0000, v10
	v_lshlrev_b32_e32 v10, 16, v11
	v_and_b32_e32 v11, 0xffff0000, v11
	s_waitcnt vmcnt(13)
	v_lshlrev_b32_e32 v16, 16, v18
	v_and_b32_e32 v17, 0xffff0000, v18
	v_lshlrev_b32_e32 v18, 16, v19
	v_and_b32_e32 v19, 0xffff0000, v19
	s_waitcnt vmcnt(12)
	v_lshlrev_b32_e32 v12, 16, v14
	v_and_b32_e32 v13, 0xffff0000, v14
	v_lshlrev_b32_e32 v14, 16, v15
	v_and_b32_e32 v15, 0xffff0000, v15
	s_waitcnt vmcnt(11)
	v_lshlrev_b32_e32 v20, 16, v22
	v_and_b32_e32 v21, 0xffff0000, v22
	v_lshlrev_b32_e32 v22, 16, v23
	v_and_b32_e32 v23, 0xffff0000, v23
	s_waitcnt vmcnt(10)
	v_lshlrev_b32_e32 v24, 16, v26
	v_and_b32_e32 v25, 0xffff0000, v26
	v_lshlrev_b32_e32 v26, 16, v27
	v_and_b32_e32 v27, 0xffff0000, v27
	s_waitcnt vmcnt(9)
	v_lshlrev_b32_e32 v28, 16, v30
	v_and_b32_e32 v29, 0xffff0000, v30
	v_lshlrev_b32_e32 v30, 16, v31
	v_and_b32_e32 v31, 0xffff0000, v31
	s_waitcnt vmcnt(8)
	v_lshlrev_b32_e32 v32, 16, v34
	v_and_b32_e32 v33, 0xffff0000, v34
	v_lshlrev_b32_e32 v34, 16, v35
	v_and_b32_e32 v35, 0xffff0000, v35
	s_waitcnt vmcnt(7)
	v_lshlrev_b32_e32 v52, 16, v36
	v_and_b32_e32 v53, 0xffff0000, v36
	v_pk_add_f32 v[4:5], v[4:5], v[52:53]
	v_lshlrev_b32_e32 v52, 16, v37
	v_and_b32_e32 v53, 0xffff0000, v37
	v_pk_add_f32 v[6:7], v[6:7], v[52:53]
	s_waitcnt vmcnt(6)
	v_lshlrev_b32_e32 v52, 16, v38
	v_and_b32_e32 v53, 0xffff0000, v38
	v_pk_add_f32 v[8:9], v[8:9], v[52:53]
	v_lshlrev_b32_e32 v52, 16, v39
	v_and_b32_e32 v53, 0xffff0000, v39
	v_pk_add_f32 v[10:11], v[10:11], v[52:53]
	s_waitcnt vmcnt(5)
	v_lshlrev_b32_e32 v52, 16, v40
	v_and_b32_e32 v53, 0xffff0000, v40
	v_pk_add_f32 v[16:17], v[16:17], v[52:53]
	v_lshlrev_b32_e32 v52, 16, v41
	v_and_b32_e32 v53, 0xffff0000, v41
	v_pk_add_f32 v[18:19], v[18:19], v[52:53]
	s_waitcnt vmcnt(4)
	v_lshlrev_b32_e32 v52, 16, v42
	v_and_b32_e32 v53, 0xffff0000, v42
	v_pk_add_f32 v[12:13], v[12:13], v[52:53]
	v_lshlrev_b32_e32 v52, 16, v43
	v_and_b32_e32 v53, 0xffff0000, v43
	v_pk_add_f32 v[14:15], v[14:15], v[52:53]
	s_waitcnt vmcnt(3)
	v_lshlrev_b32_e32 v52, 16, v44
	v_and_b32_e32 v53, 0xffff0000, v44
	v_pk_add_f32 v[20:21], v[20:21], v[52:53]
	v_lshlrev_b32_e32 v52, 16, v45
	v_and_b32_e32 v53, 0xffff0000, v45
	v_pk_add_f32 v[22:23], v[22:23], v[52:53]
	s_waitcnt vmcnt(2)
	v_lshlrev_b32_e32 v52, 16, v46
	v_and_b32_e32 v53, 0xffff0000, v46
	v_pk_add_f32 v[24:25], v[24:25], v[52:53]
	v_lshlrev_b32_e32 v52, 16, v47
	v_and_b32_e32 v53, 0xffff0000, v47
	v_pk_add_f32 v[26:27], v[26:27], v[52:53]
	s_waitcnt vmcnt(1)
	v_lshlrev_b32_e32 v52, 16, v48
	v_and_b32_e32 v53, 0xffff0000, v48
	v_pk_add_f32 v[28:29], v[28:29], v[52:53]
	v_lshlrev_b32_e32 v52, 16, v49
	v_and_b32_e32 v53, 0xffff0000, v49
	v_pk_add_f32 v[30:31], v[30:31], v[52:53]
	s_waitcnt vmcnt(0)
	v_lshlrev_b32_e32 v52, 16, v50
	v_and_b32_e32 v53, 0xffff0000, v50
	v_pk_add_f32 v[32:33], v[32:33], v[52:53]
	v_lshlrev_b32_e32 v52, 16, v51
	v_and_b32_e32 v53, 0xffff0000, v51
	v_pk_add_f32 v[34:35], v[34:35], v[52:53]
	s_add_u32 s14, s14, 0x400000
	s_addc_u32 s15, s15, 0
	v_lshlrev_b32_e32 v52, 3, v174
	global_load_dwordx2 v[36:37], v52, s[14:15] offset:0
	global_load_dwordx2 v[38:39], v52, s[14:15] offset:512
	global_load_dwordx2 v[40:41], v52, s[14:15] offset:1024
	global_load_dwordx2 v[42:43], v52, s[14:15] offset:1536
	global_load_dwordx2 v[44:45], v52, s[14:15] offset:2048
	global_load_dwordx2 v[46:47], v52, s[14:15] offset:2560
	global_load_dwordx2 v[48:49], v52, s[14:15] offset:3072
	global_load_dwordx2 v[50:51], v52, s[14:15] offset:3584
	s_waitcnt vmcnt(7)
	v_lshlrev_b32_e32 v52, 16, v36
	v_and_b32_e32 v53, 0xffff0000, v36
	v_pk_add_f32 v[4:5], v[4:5], v[52:53]
	v_lshlrev_b32_e32 v52, 16, v37
	v_and_b32_e32 v53, 0xffff0000, v37
	v_pk_add_f32 v[6:7], v[6:7], v[52:53]
	s_waitcnt vmcnt(6)
	v_lshlrev_b32_e32 v52, 16, v38
	v_and_b32_e32 v53, 0xffff0000, v38
	v_pk_add_f32 v[8:9], v[8:9], v[52:53]
	v_lshlrev_b32_e32 v52, 16, v39
	v_and_b32_e32 v53, 0xffff0000, v39
	v_pk_add_f32 v[10:11], v[10:11], v[52:53]
	s_waitcnt vmcnt(5)
	v_lshlrev_b32_e32 v52, 16, v40
	v_and_b32_e32 v53, 0xffff0000, v40
	v_pk_add_f32 v[16:17], v[16:17], v[52:53]
	v_lshlrev_b32_e32 v52, 16, v41
	v_and_b32_e32 v53, 0xffff0000, v41
	v_pk_add_f32 v[18:19], v[18:19], v[52:53]
	s_waitcnt vmcnt(4)
; __device__ __forceinline__ f32x4 ld_bf4(const bf16* p) { const u32x2 w = *(const u32x2*)p; return (f32x4){__builtin_bit_cast(float, w.x << 16), __builtin_bit_cast(float, w.x & 0xffff0000u), __builtin_bit_cast(float, w.y << 16), __builtin_bit_cast(float, w.y & 0xffff0000u)}; }
; __device__ __forceinline__ void rowwise_phase(const Params& P, int mrows, bool first, int l_post, int j_post, int gate_idx, float coef, bool final_, int l_pre, int j_pre, int shift_idx, int scale_idx) {
;     ...
;                 for (int ks = 1; ks < 8; ++ks) {
; #pragma unroll
;                     for (int j = 0; j < 8; ++j) yv[j] += ld_bf4(pr + (size_t)ks * MCTX * DM + 4 * lane + 256 * j);
;                 }
	v_lshlrev_b32_e32 v52, 16, v42
	v_and_b32_e32 v53, 0xffff0000, v42
	v_pk_add_f32 v[12:13], v[12:13], v[52:53]
	v_lshlrev_b32_e32 v52, 16, v43
	v_and_b32_e32 v53, 0xffff0000, v43
	v_pk_add_f32 v[14:15], v[14:15], v[52:53]
	s_waitcnt vmcnt(3)
	v_lshlrev_b32_e32 v52, 16, v44
	v_and_b32_e32 v53, 0xffff0000, v44
	v_pk_add_f32 v[20:21], v[20:21], v[52:53]
	v_lshlrev_b32_e32 v52, 16, v45
	v_and_b32_e32 v53, 0xffff0000, v45
	v_pk_add_f32 v[22:23], v[22:23], v[52:53]
	s_waitcnt vmcnt(2)
	v_lshlrev_b32_e32 v52, 16, v46
	v_and_b32_e32 v53, 0xffff0000, v46
	v_pk_add_f32 v[24:25], v[24:25], v[52:53]
	v_lshlrev_b32_e32 v52, 16, v47
	v_and_b32_e32 v53, 0xffff0000, v47
	v_pk_add_f32 v[26:27], v[26:27], v[52:53]
	s_waitcnt vmcnt(1)
	v_lshlrev_b32_e32 v52, 16, v48
	v_and_b32_e32 v53, 0xffff0000, v48
	v_pk_add_f32 v[28:29], v[28:29], v[52:53]
	v_lshlrev_b32_e32 v52, 16, v49
	v_and_b32_e32 v53, 0xffff0000, v49
	v_pk_add_f32 v[30:31], v[30:31], v[52:53]
	s_waitcnt vmcnt(0)
	v_lshlrev_b32_e32 v52, 16, v50
	v_and_b32_e32 v53, 0xffff0000, v50
	v_pk_add_f32 v[32:33], v[32:33], v[52:53]
	v_lshlrev_b32_e32 v52, 16, v51
	v_and_b32_e32 v53, 0xffff0000, v51
	v_pk_add_f32 v[34:35], v[34:35], v[52:53]
	s_add_u32 s14, s14, 0x400000
	s_addc_u32 s15, s15, 0
	v_lshlrev_b32_e32 v52, 3, v174
	global_load_dwordx2 v[36:37], v52, s[14:15] offset:0
	global_load_dwordx2 v[38:39], v52, s[14:15] offset:512
	global_load_dwordx2 v[40:41], v52, s[14:15] offset:1024
	global_load_dwordx2 v[42:43], v52, s[14:15] offset:1536
	global_load_dwordx2 v[44:45], v52, s[14:15] offset:2048
	global_load_dwordx2 v[46:47], v52, s[14:15] offset:2560
	global_load_dwordx2 v[48:49], v52, s[14:15] offset:3072
	global_load_dwordx2 v[50:51], v52, s[14:15] offset:3584
	s_waitcnt vmcnt(7)
	v_lshlrev_b32_e32 v52, 16, v36
	v_and_b32_e32 v53, 0xffff0000, v36
	v_pk_add_f32 v[4:5], v[4:5], v[52:53]
	v_lshlrev_b32_e32 v52, 16, v37
	v_and_b32_e32 v53, 0xffff0000, v37
	v_pk_add_f32 v[6:7], v[6:7], v[52:53]
	s_waitcnt vmcnt(6)
	v_lshlrev_b32_e32 v52, 16, v38
	v_and_b32_e32 v53, 0xffff0000, v38
	v_pk_add_f32 v[8:9], v[8:9], v[52:53]
	v_lshlrev_b32_e32 v52, 16, v39
	v_and_b32_e32 v53, 0xffff0000, v39
	v_pk_add_f32 v[10:11], v[10:11], v[52:53]
	s_waitcnt vmcnt(5)
	v_lshlrev_b32_e32 v52, 16, v40
	v_and_b32_e32 v53, 0xffff0000, v40
	v_pk_add_f32 v[16:17], v[16:17], v[52:53]
	v_lshlrev_b32_e32 v52, 16, v41
	v_and_b32_e32 v53, 0xffff0000, v41
	v_pk_add_f32 v[18:19], v[18:19], v[52:53]
	s_waitcnt vmcnt(4)
	v_lshlrev_b32_e32 v52, 16, v42
	v_and_b32_e32 v53, 0xffff0000, v42
	v_pk_add_f32 v[12:13], v[12:13], v[52:53]
	v_lshlrev_b32_e32 v52, 16, v43
	v_and_b32_e32 v53, 0xffff0000, v43
	v_pk_add_f32 v[14:15], v[14:15], v[52:53]
	s_waitcnt vmcnt(3)
	v_lshlrev_b32_e32 v52, 16, v44
	v_and_b32_e32 v53, 0xffff0000, v44
	v_pk_add_f32 v[20:21], v[20:21], v[52:53]
	v_lshlrev_b32_e32 v52, 16, v45
	v_and_b32_e32 v53, 0xffff0000, v45
	v_pk_add_f32 v[22:23], v[22:23], v[52:53]
	s_waitcnt vmcnt(2)
	v_lshlrev_b32_e32 v52, 16, v46
	v_and_b32_e32 v53, 0xffff0000, v46
	v_pk_add_f32 v[24:25], v[24:25], v[52:53]
	v_lshlrev_b32_e32 v52, 16, v47
	v_and_b32_e32 v53, 0xffff0000, v47
	v_pk_add_f32 v[26:27], v[26:27], v[52:53]
	s_waitcnt vmcnt(1)
	v_lshlrev_b32_e32 v52, 16, v48
	v_and_b32_e32 v53, 0xffff0000, v48
	v_pk_add_f32 v[28:29], v[28:29], v[52:53]
	v_lshlrev_b32_e32 v52, 16, v49
	v_and_b32_e32 v53, 0xffff0000, v49
	v_pk_add_f32 v[30:31], v[30:31], v[52:53]
	s_waitcnt vmcnt(0)
	v_lshlrev_b32_e32 v52, 16, v50
	v_and_b32_e32 v53, 0xffff0000, v50
	v_pk_add_f32 v[32:33], v[32:33], v[52:53]
	v_lshlrev_b32_e32 v52, 16, v51
	v_and_b32_e32 v53, 0xffff0000, v51
	v_pk_add_f32 v[34:35], v[34:35], v[52:53]
	s_add_u32 s14, s14, 0x400000
	s_addc_u32 s15, s15, 0
	v_lshlrev_b32_e32 v52, 3, v174
	global_load_dwordx2 v[36:37], v52, s[14:15] offset:0
	global_load_dwordx2 v[38:39], v52, s[14:15] offset:512
	global_load_dwordx2 v[40:41], v52, s[14:15] offset:1024
	global_load_dwordx2 v[42:43], v52, s[14:15] offset:1536
	global_load_dwordx2 v[44:45], v52, s[14:15] offset:2048
	global_load_dwordx2 v[46:47], v52, s[14:15] offset:2560
	global_load_dwordx2 v[48:49], v52, s[14:15] offset:3072
	global_load_dwordx2 v[50:51], v52, s[14:15] offset:3584
	s_waitcnt vmcnt(7)
	v_lshlrev_b32_e32 v52, 16, v36
	v_and_b32_e32 v53, 0xffff0000, v36
	v_pk_add_f32 v[4:5], v[4:5], v[52:53]
	v_lshlrev_b32_e32 v52, 16, v37
	v_and_b32_e32 v53, 0xffff0000, v37
	v_pk_add_f32 v[6:7], v[6:7], v[52:53]
	s_waitcnt vmcnt(6)
	v_lshlrev_b32_e32 v52, 16, v38
	v_and_b32_e32 v53, 0xffff0000, v38
	v_pk_add_f32 v[8:9], v[8:9], v[52:53]
	v_lshlrev_b32_e32 v52, 16, v39
	v_and_b32_e32 v53, 0xffff0000, v39
	v_pk_add_f32 v[10:11], v[10:11], v[52:53]
	s_waitcnt vmcnt(5)
	v_lshlrev_b32_e32 v52, 16, v40
	v_and_b32_e32 v53, 0xffff0000, v40
	v_pk_add_f32 v[16:17], v[16:17], v[52:53]
	v_lshlrev_b32_e32 v52, 16, v41
	v_and_b32_e32 v53, 0xffff0000, v41
	v_pk_add_f32 v[18:19], v[18:19], v[52:53]
	s_waitcnt vmcnt(4)
	v_lshlrev_b32_e32 v52, 16, v42
	v_and_b32_e32 v53, 0xffff0000, v42
	v_pk_add_f32 v[12:13], v[12:13], v[52:53]
	v_lshlrev_b32_e32 v52, 16, v43
	v_and_b32_e32 v53, 0xffff0000, v43
	v_pk_add_f32 v[14:15], v[14:15], v[52:53]
	s_waitcnt vmcnt(3)
	v_lshlrev_b32_e32 v52, 16, v44
	v_and_b32_e32 v53, 0xffff0000, v44
	v_pk_add_f32 v[20:21], v[20:21], v[52:53]
	v_lshlrev_b32_e32 v52, 16, v45
	v_and_b32_e32 v53, 0xffff0000, v45
	v_pk_add_f32 v[22:23], v[22:23], v[52:53]
	s_waitcnt vmcnt(2)
	v_lshlrev_b32_e32 v52, 16, v46
	v_and_b32_e32 v53, 0xffff0000, v46
	v_pk_add_f32 v[24:25], v[24:25], v[52:53]
	v_lshlrev_b32_e32 v52, 16, v47
	v_and_b32_e32 v53, 0xffff0000, v47
	v_pk_add_f32 v[26:27], v[26:27], v[52:53]
	s_waitcnt vmcnt(1)
; __device__ __forceinline__ f32x4 ld_bf4(const bf16* p) { const u32x2 w = *(const u32x2*)p; return (f32x4){__builtin_bit_cast(float, w.x << 16), __builtin_bit_cast(float, w.x & 0xffff0000u), __builtin_bit_cast(float, w.y << 16), __builtin_bit_cast(float, w.y & 0xffff0000u)}; }
; __device__ __forceinline__ void rowwise_phase(const Params& P, int mrows, bool first, int l_post, int j_post, int gate_idx, float coef, bool final_, int l_pre, int j_pre, int shift_idx, int scale_idx) {
;     ...
;                 for (int ks = 1; ks < 8; ++ks) {
; #pragma unroll
;                     for (int j = 0; j < 8; ++j) yv[j] += ld_bf4(pr + (size_t)ks * MCTX * DM + 4 * lane + 256 * j);
;                 }
	v_lshlrev_b32_e32 v52, 16, v48
	v_and_b32_e32 v53, 0xffff0000, v48
	v_pk_add_f32 v[28:29], v[28:29], v[52:53]
	v_lshlrev_b32_e32 v52, 16, v49
	v_and_b32_e32 v53, 0xffff0000, v49
	v_pk_add_f32 v[30:31], v[30:31], v[52:53]
	s_waitcnt vmcnt(0)
	v_lshlrev_b32_e32 v52, 16, v50
	v_and_b32_e32 v53, 0xffff0000, v50
	v_pk_add_f32 v[32:33], v[32:33], v[52:53]
	v_lshlrev_b32_e32 v52, 16, v51
	v_and_b32_e32 v53, 0xffff0000, v51
	v_pk_add_f32 v[34:35], v[34:35], v[52:53]
	s_add_u32 s14, s14, 0x400000
	s_addc_u32 s15, s15, 0
	v_lshlrev_b32_e32 v52, 3, v174
	global_load_dwordx2 v[36:37], v52, s[14:15] offset:0
	global_load_dwordx2 v[38:39], v52, s[14:15] offset:512
	global_load_dwordx2 v[40:41], v52, s[14:15] offset:1024
	global_load_dwordx2 v[42:43], v52, s[14:15] offset:1536
	global_load_dwordx2 v[44:45], v52, s[14:15] offset:2048
	global_load_dwordx2 v[46:47], v52, s[14:15] offset:2560
	global_load_dwordx2 v[48:49], v52, s[14:15] offset:3072
	global_load_dwordx2 v[50:51], v52, s[14:15] offset:3584
	s_waitcnt vmcnt(7)
	v_lshlrev_b32_e32 v52, 16, v36
	v_and_b32_e32 v53, 0xffff0000, v36
	v_pk_add_f32 v[4:5], v[4:5], v[52:53]
	v_lshlrev_b32_e32 v52, 16, v37
	v_and_b32_e32 v53, 0xffff0000, v37
	v_pk_add_f32 v[6:7], v[6:7], v[52:53]
	s_waitcnt vmcnt(6)
	v_lshlrev_b32_e32 v52, 16, v38
	v_and_b32_e32 v53, 0xffff0000, v38
	v_pk_add_f32 v[8:9], v[8:9], v[52:53]
	v_lshlrev_b32_e32 v52, 16, v39
	v_and_b32_e32 v53, 0xffff0000, v39
	v_pk_add_f32 v[10:11], v[10:11], v[52:53]
	s_waitcnt vmcnt(5)
	v_lshlrev_b32_e32 v52, 16, v40
	v_and_b32_e32 v53, 0xffff0000, v40
	v_pk_add_f32 v[16:17], v[16:17], v[52:53]
	v_lshlrev_b32_e32 v52, 16, v41
	v_and_b32_e32 v53, 0xffff0000, v41
	v_pk_add_f32 v[18:19], v[18:19], v[52:53]
	s_waitcnt vmcnt(4)
	v_lshlrev_b32_e32 v52, 16, v42
	v_and_b32_e32 v53, 0xffff0000, v42
	v_pk_add_f32 v[12:13], v[12:13], v[52:53]
	v_lshlrev_b32_e32 v52, 16, v43
	v_and_b32_e32 v53, 0xffff0000, v43
	v_pk_add_f32 v[14:15], v[14:15], v[52:53]
	s_waitcnt vmcnt(3)
	v_lshlrev_b32_e32 v52, 16, v44
	v_and_b32_e32 v53, 0xffff0000, v44
	v_pk_add_f32 v[20:21], v[20:21], v[52:53]
	v_lshlrev_b32_e32 v52, 16, v45
	v_and_b32_e32 v53, 0xffff0000, v45
	v_pk_add_f32 v[22:23], v[22:23], v[52:53]
	s_waitcnt vmcnt(2)
	v_lshlrev_b32_e32 v52, 16, v46
	v_and_b32_e32 v53, 0xffff0000, v46
	v_pk_add_f32 v[24:25], v[24:25], v[52:53]
	v_lshlrev_b32_e32 v52, 16, v47
	v_and_b32_e32 v53, 0xffff0000, v47
	v_pk_add_f32 v[26:27], v[26:27], v[52:53]
	s_waitcnt vmcnt(1)
	v_lshlrev_b32_e32 v52, 16, v48
	v_and_b32_e32 v53, 0xffff0000, v48
	v_pk_add_f32 v[28:29], v[28:29], v[52:53]
	v_lshlrev_b32_e32 v52, 16, v49
	v_and_b32_e32 v53, 0xffff0000, v49
	v_pk_add_f32 v[30:31], v[30:31], v[52:53]
	s_waitcnt vmcnt(0)
	v_lshlrev_b32_e32 v52, 16, v50
	v_and_b32_e32 v53, 0xffff0000, v50
	v_pk_add_f32 v[32:33], v[32:33], v[52:53]
	v_lshlrev_b32_e32 v52, 16, v51
	v_and_b32_e32 v53, 0xffff0000, v51
	v_pk_add_f32 v[34:35], v[34:35], v[52:53]
	s_add_u32 s14, s14, 0x400000
	s_addc_u32 s15, s15, 0
	v_lshlrev_b32_e32 v52, 3, v174
	global_load_dwordx2 v[36:37], v52, s[14:15] offset:0
	global_load_dwordx2 v[38:39], v52, s[14:15] offset:512
	global_load_dwordx2 v[40:41], v52, s[14:15] offset:1024
	global_load_dwordx2 v[42:43], v52, s[14:15] offset:1536
	global_load_dwordx2 v[44:45], v52, s[14:15] offset:2048
	global_load_dwordx2 v[46:47], v52, s[14:15] offset:2560
	global_load_dwordx2 v[48:49], v52, s[14:15] offset:3072
	global_load_dwordx2 v[50:51], v52, s[14:15] offset:3584
	s_waitcnt vmcnt(7)
	v_lshlrev_b32_e32 v52, 16, v36
	v_and_b32_e32 v53, 0xffff0000, v36
	v_pk_add_f32 v[4:5], v[4:5], v[52:53]
	v_lshlrev_b32_e32 v52, 16, v37
	v_and_b32_e32 v53, 0xffff0000, v37
	v_pk_add_f32 v[6:7], v[6:7], v[52:53]
	s_waitcnt vmcnt(6)
	v_lshlrev_b32_e32 v52, 16, v38
	v_and_b32_e32 v53, 0xffff0000, v38
	v_pk_add_f32 v[8:9], v[8:9], v[52:53]
	v_lshlrev_b32_e32 v52, 16, v39
	v_and_b32_e32 v53, 0xffff0000, v39
	v_pk_add_f32 v[10:11], v[10:11], v[52:53]
	s_waitcnt vmcnt(5)
; __device__ __forceinline__ f32x4 ld_bf4(const bf16* p) { const u32x2 w = *(const u32x2*)p; return (f32x4){__builtin_bit_cast(float, w.x << 16), __builtin_bit_cast(float, w.x & 0xffff0000u), __builtin_bit_cast(float, w.y << 16), __builtin_bit_cast(float, w.y & 0xffff0000u)}; }
; __device__ __forceinline__ void rowwise_phase(const Params& P, int mrows, bool first, int l_post, int j_post, int gate_idx, float coef, bool final_, int l_pre, int j_pre, int shift_idx, int scale_idx) {
;     ...
;                 for (int ks = 1; ks < 8; ++ks) {
; #pragma unroll
;                     for (int j = 0; j < 8; ++j) yv[j] += ld_bf4(pr + (size_t)ks * MCTX * DM + 4 * lane + 256 * j);
;                 }
	v_lshlrev_b32_e32 v52, 16, v40
	v_and_b32_e32 v53, 0xffff0000, v40
	v_pk_add_f32 v[16:17], v[16:17], v[52:53]
	v_lshlrev_b32_e32 v52, 16, v41
	v_and_b32_e32 v53, 0xffff0000, v41
	v_pk_add_f32 v[18:19], v[18:19], v[52:53]
	s_waitcnt vmcnt(4)
	v_lshlrev_b32_e32 v52, 16, v42
	v_and_b32_e32 v53, 0xffff0000, v42
	v_pk_add_f32 v[12:13], v[12:13], v[52:53]
	v_lshlrev_b32_e32 v52, 16, v43
	v_and_b32_e32 v53, 0xffff0000, v43
	v_pk_add_f32 v[14:15], v[14:15], v[52:53]
	s_waitcnt vmcnt(3)
	v_lshlrev_b32_e32 v52, 16, v44
	v_and_b32_e32 v53, 0xffff0000, v44
	v_pk_add_f32 v[20:21], v[20:21], v[52:53]
	v_lshlrev_b32_e32 v52, 16, v45
	v_and_b32_e32 v53, 0xffff0000, v45
	v_pk_add_f32 v[22:23], v[22:23], v[52:53]
	s_waitcnt vmcnt(2)
	v_lshlrev_b32_e32 v52, 16, v46
	v_and_b32_e32 v53, 0xffff0000, v46
	v_pk_add_f32 v[24:25], v[24:25], v[52:53]
	v_lshlrev_b32_e32 v52, 16, v47
	v_and_b32_e32 v53, 0xffff0000, v47
	v_pk_add_f32 v[26:27], v[26:27], v[52:53]
	s_waitcnt vmcnt(1)
	v_lshlrev_b32_e32 v52, 16, v48
	v_and_b32_e32 v53, 0xffff0000, v48
	v_pk_add_f32 v[28:29], v[28:29], v[52:53]
	v_lshlrev_b32_e32 v52, 16, v49
	v_and_b32_e32 v53, 0xffff0000, v49
	v_pk_add_f32 v[30:31], v[30:31], v[52:53]
	s_waitcnt vmcnt(0)
	v_lshlrev_b32_e32 v52, 16, v50
	v_and_b32_e32 v53, 0xffff0000, v50
	v_pk_add_f32 v[32:33], v[32:33], v[52:53]
	v_lshlrev_b32_e32 v52, 16, v51
	v_and_b32_e32 v53, 0xffff0000, v51
	v_pk_add_f32 v[34:35], v[34:35], v[52:53]
	s_add_u32 s14, s14, 0x400000
	s_addc_u32 s15, s15, 0
	v_lshlrev_b32_e32 v52, 3, v174
	global_load_dwordx2 v[36:37], v52, s[14:15] offset:0
	global_load_dwordx2 v[38:39], v52, s[14:15] offset:512
	global_load_dwordx2 v[40:41], v52, s[14:15] offset:1024
	global_load_dwordx2 v[42:43], v52, s[14:15] offset:1536
	global_load_dwordx2 v[44:45], v52, s[14:15] offset:2048
	global_load_dwordx2 v[46:47], v52, s[14:15] offset:2560
	global_load_dwordx2 v[48:49], v52, s[14:15] offset:3072
	global_load_dwordx2 v[50:51], v52, s[14:15] offset:3584
	s_waitcnt vmcnt(7)
	v_lshlrev_b32_e32 v52, 16, v36
	v_and_b32_e32 v53, 0xffff0000, v36
	v_pk_add_f32 v[4:5], v[4:5], v[52:53]
	v_lshlrev_b32_e32 v52, 16, v37
	v_and_b32_e32 v53, 0xffff0000, v37
	v_pk_add_f32 v[6:7], v[6:7], v[52:53]
	s_waitcnt vmcnt(6)
	v_lshlrev_b32_e32 v52, 16, v38
	v_and_b32_e32 v53, 0xffff0000, v38
	v_pk_add_f32 v[8:9], v[8:9], v[52:53]
	v_lshlrev_b32_e32 v52, 16, v39
	v_and_b32_e32 v53, 0xffff0000, v39
	v_pk_add_f32 v[10:11], v[10:11], v[52:53]
	s_waitcnt vmcnt(5)
	v_lshlrev_b32_e32 v52, 16, v40
	v_and_b32_e32 v53, 0xffff0000, v40
	v_pk_add_f32 v[16:17], v[16:17], v[52:53]
	v_lshlrev_b32_e32 v52, 16, v41
	v_and_b32_e32 v53, 0xffff0000, v41
	v_pk_add_f32 v[18:19], v[18:19], v[52:53]
	s_waitcnt vmcnt(4)
	v_lshlrev_b32_e32 v52, 16, v42
	v_and_b32_e32 v53, 0xffff0000, v42
	v_pk_add_f32 v[12:13], v[12:13], v[52:53]
	v_lshlrev_b32_e32 v52, 16, v43
	v_and_b32_e32 v53, 0xffff0000, v43
	v_pk_add_f32 v[14:15], v[14:15], v[52:53]
	s_waitcnt vmcnt(3)
	v_lshlrev_b32_e32 v52, 16, v44
	v_and_b32_e32 v53, 0xffff0000, v44
	v_pk_add_f32 v[20:21], v[20:21], v[52:53]
	v_lshlrev_b32_e32 v52, 16, v45
	v_and_b32_e32 v53, 0xffff0000, v45
	v_pk_add_f32 v[22:23], v[22:23], v[52:53]
	s_waitcnt vmcnt(2)
	v_lshlrev_b32_e32 v52, 16, v46
	v_and_b32_e32 v53, 0xffff0000, v46
	v_pk_add_f32 v[24:25], v[24:25], v[52:53]
	v_lshlrev_b32_e32 v52, 16, v47
	v_and_b32_e32 v53, 0xffff0000, v47
	v_pk_add_f32 v[26:27], v[26:27], v[52:53]
	s_waitcnt vmcnt(1)
	v_lshlrev_b32_e32 v52, 16, v48
	v_and_b32_e32 v53, 0xffff0000, v48
	v_pk_add_f32 v[28:29], v[28:29], v[52:53]
	v_lshlrev_b32_e32 v52, 16, v49
	v_and_b32_e32 v53, 0xffff0000, v49
	v_pk_add_f32 v[30:31], v[30:31], v[52:53]
	s_waitcnt vmcnt(0)
	v_lshlrev_b32_e32 v52, 16, v50
	v_and_b32_e32 v53, 0xffff0000, v50
	v_pk_add_f32 v[32:33], v[32:33], v[52:53]
	v_lshlrev_b32_e32 v52, 16, v51
	v_and_b32_e32 v53, 0xffff0000, v51
	v_pk_add_f32 v[34:35], v[34:35], v[52:53]
	s_mov_b64 s[14:15], 0

; __device__ __forceinline__ f32x4 ld_bf4(const bf16* p) { const u32x2 w = *(const u32x2*)p; return (f32x4){__builtin_bit_cast(float, w.x << 16), __builtin_bit_cast(float, w.x & 0xffff0000u), __builtin_bit_cast(float, w.y << 16), __builtin_bit_cast(float, w.y & 0xffff0000u)}; }
; __device__ __forceinline__ void rowwise_phase(const Params& P, int mrows, bool first, int l_post, int j_post, int gate_idx, float coef, bool final_, int l_pre, int j_pre, int shift_idx, int scale_idx) {
;     ...
;             if (row < MLAT) {
;                 const bf16* yb = (const bf16*)Y + (size_t)row * DM;
; #pragma unroll
;                 for (int j = 0; j < 8; ++j) { const u32x2 w = *(const u32x2*)(yb + 4 * lane + 256 * j);
;                     yv[j] = (f32x4){__builtin_bit_cast(float, w.x << 16), __builtin_bit_cast(float, w.x & 0xffff0000u), __builtin_bit_cast(float, w.y << 16), __builtin_bit_cast(float, w.y & 0xffff0000u)}; }
;             } else {
;                 const bf16* pr = (const bf16*)(P.ws + WS_YD) + (size_t)(row - MLAT) * DM;
; #pragma unroll
;                 for (int j = 0; j < 8; ++j) yv[j] = ld_bf4(pr + 4 * lane + 256 * j);
;                 for (int ks = 1; ks < 8; ++ks) {
; #pragma unroll
;                     for (int j = 0; j < 8; ++j) yv[j] += ld_bf4(pr + (size_t)ks * MCTX * DM + 4 * lane + 256 * j);
;                 }
.LBB0_37:
	s_cmpk_gt_i32 s0, 0x1fff
	s_mov_b64 s[10:11], -1
	s_cbranch_scc0 .LBB0_39
	s_add_i32 s58, s0, 0xffffe000
	s_lshl_b64 s[10:11], s[58:59], 12
	s_add_u32 s10, s10, s94
	s_addc_u32 s11, s11, s95
	s_add_u32 s10, s10, 0x34f00000
	s_addc_u32 s11, s11, 0
	v_lshlrev_b32_e32 v52, 3, v174
	global_load_dwordx2 v[6:7], v52, s[10:11] offset:0
	global_load_dwordx2 v[10:11], v52, s[10:11] offset:512
	global_load_dwordx2 v[18:19], v52, s[10:11] offset:1024
	global_load_dwordx2 v[14:15], v52, s[10:11] offset:1536
	global_load_dwordx2 v[22:23], v52, s[10:11] offset:2048
	global_load_dwordx2 v[26:27], v52, s[10:11] offset:2560
	global_load_dwordx2 v[30:31], v52, s[10:11] offset:3072
	global_load_dwordx2 v[34:35], v52, s[10:11] offset:3584
	s_add_u32 s10, s10, 0x400000
	s_addc_u32 s11, s11, 0
	global_load_dwordx2 v[36:37], v52, s[10:11] offset:0
	global_load_dwordx2 v[38:39], v52, s[10:11] offset:512
	global_load_dwordx2 v[40:41], v52, s[10:11] offset:1024
	global_load_dwordx2 v[42:43], v52, s[10:11] offset:1536
	global_load_dwordx2 v[44:45], v52, s[10:11] offset:2048
	global_load_dwordx2 v[46:47], v52, s[10:11] offset:2560
	global_load_dwordx2 v[48:49], v52, s[10:11] offset:3072
	global_load_dwordx2 v[50:51], v52, s[10:11] offset:3584
	s_waitcnt vmcnt(15)
	v_lshlrev_b32_e32 v4, 16, v6
	v_and_b32_e32 v5, 0xffff0000, v6
	v_lshlrev_b32_e32 v6, 16, v7
	v_and_b32_e32 v7, 0xffff0000, v7
	s_waitcnt vmcnt(14)
	v_lshlrev_b32_e32 v8, 16, v10
	v_and_b32_e32 v9, 0xffff0000, v10
	v_lshlrev_b32_e32 v10, 16, v11
	v_and_b32_e32 v11, 0xffff0000, v11
	s_waitcnt vmcnt(13)
	v_lshlrev_b32_e32 v16, 16, v18
	v_and_b32_e32 v17, 0xffff0000, v18
	v_lshlrev_b32_e32 v18, 16, v19
	v_and_b32_e32 v19, 0xffff0000, v19
	s_waitcnt vmcnt(12)
	v_lshlrev_b32_e32 v12, 16, v14
	v_and_b32_e32 v13, 0xffff0000, v14
	v_lshlrev_b32_e32 v14, 16, v15
	v_and_b32_e32 v15, 0xffff0000, v15
	s_waitcnt vmcnt(11)
	v_lshlrev_b32_e32 v20, 16, v22
	v_and_b32_e32 v21, 0xffff0000, v22
	v_lshlrev_b32_e32 v22, 16, v23
	v_and_b32_e32 v23, 0xffff0000, v23
	s_waitcnt vmcnt(10)
	v_lshlrev_b32_e32 v24, 16, v26
	v_and_b32_e32 v25, 0xffff0000, v26
	v_lshlrev_b32_e32 v26, 16, v27
	v_and_b32_e32 v27, 0xffff0000, v27
	s_waitcnt vmcnt(9)
	v_lshlrev_b32_e32 v28, 16, v30
	v_and_b32_e32 v29, 0xffff0000, v30
	v_lshlrev_b32_e32 v30, 16, v31
	v_and_b32_e32 v31, 0xffff0000, v31
	s_waitcnt vmcnt(8)
	v_lshlrev_b32_e32 v32, 16, v34
	v_and_b32_e32 v33, 0xffff0000, v34
	v_lshlrev_b32_e32 v34, 16, v35
	v_and_b32_e32 v35, 0xffff0000, v35
	s_waitcnt vmcnt(7)
	v_lshlrev_b32_e32 v52, 16, v36
	v_and_b32_e32 v53, 0xffff0000, v36
	v_pk_add_f32 v[4:5], v[4:5], v[52:53]
	v_lshlrev_b32_e32 v52, 16, v37
	v_and_b32_e32 v53, 0xffff0000, v37
	v_pk_add_f32 v[6:7], v[6:7], v[52:53]
	s_waitcnt vmcnt(6)
	v_lshlrev_b32_e32 v52, 16, v38
	v_and_b32_e32 v53, 0xffff0000, v38
	v_pk_add_f32 v[8:9], v[8:9], v[52:53]
	v_lshlrev_b32_e32 v52, 16, v39
	v_and_b32_e32 v53, 0xffff0000, v39
	v_pk_add_f32 v[10:11], v[10:11], v[52:53]
	s_waitcnt vmcnt(5)
	v_lshlrev_b32_e32 v52, 16, v40
	v_and_b32_e32 v53, 0xffff0000, v40
	v_pk_add_f32 v[16:17], v[16:17], v[52:53]
	v_lshlrev_b32_e32 v52, 16, v41
	v_and_b32_e32 v53, 0xffff0000, v41
	v_pk_add_f32 v[18:19], v[18:19], v[52:53]
	s_waitcnt vmcnt(4)
	v_lshlrev_b32_e32 v52, 16, v42
	v_and_b32_e32 v53, 0xffff0000, v42
	v_pk_add_f32 v[12:13], v[12:13], v[52:53]
	v_lshlrev_b32_e32 v52, 16, v43
	v_and_b32_e32 v53, 0xffff0000, v43
	v_pk_add_f32 v[14:15], v[14:15], v[52:53]
	s_waitcnt vmcnt(3)
	v_lshlrev_b32_e32 v52, 16, v44
	v_and_b32_e32 v53, 0xffff0000, v44
	v_pk_add_f32 v[20:21], v[20:21], v[52:53]
	v_lshlrev_b32_e32 v52, 16, v45
	v_and_b32_e32 v53, 0xffff0000, v45
	v_pk_add_f32 v[22:23], v[22:23], v[52:53]
	s_waitcnt vmcnt(2)
	v_lshlrev_b32_e32 v52, 16, v46
	v_and_b32_e32 v53, 0xffff0000, v46
	v_pk_add_f32 v[24:25], v[24:25], v[52:53]
	v_lshlrev_b32_e32 v52, 16, v47
	v_and_b32_e32 v53, 0xffff0000, v47
	v_pk_add_f32 v[26:27], v[26:27], v[52:53]
	s_waitcnt vmcnt(1)
	v_lshlrev_b32_e32 v52, 16, v48
	v_and_b32_e32 v53, 0xffff0000, v48
	v_pk_add_f32 v[28:29], v[28:29], v[52:53]
	v_lshlrev_b32_e32 v52, 16, v49
	v_and_b32_e32 v53, 0xffff0000, v49
	v_pk_add_f32 v[30:31], v[30:31], v[52:53]
	s_waitcnt vmcnt(0)
	v_lshlrev_b32_e32 v52, 16, v50
	v_and_b32_e32 v53, 0xffff0000, v50
	v_pk_add_f32 v[32:33], v[32:33], v[52:53]
	v_lshlrev_b32_e32 v52, 16, v51
	v_and_b32_e32 v53, 0xffff0000, v51
	v_pk_add_f32 v[34:35], v[34:35], v[52:53]
	s_add_u32 s10, s10, 0x400000
	s_addc_u32 s11, s11, 0
	v_lshlrev_b32_e32 v52, 3, v174
	global_load_dwordx2 v[36:37], v52, s[10:11] offset:0
	global_load_dwordx2 v[38:39], v52, s[10:11] offset:512
	global_load_dwordx2 v[40:41], v52, s[10:11] offset:1024
	global_load_dwordx2 v[42:43], v52, s[10:11] offset:1536
	global_load_dwordx2 v[44:45], v52, s[10:11] offset:2048
	global_load_dwordx2 v[46:47], v52, s[10:11] offset:2560
	global_load_dwordx2 v[48:49], v52, s[10:11] offset:3072
	global_load_dwordx2 v[50:51], v52, s[10:11] offset:3584
	s_waitcnt vmcnt(7)
	v_lshlrev_b32_e32 v52, 16, v36
	v_and_b32_e32 v53, 0xffff0000, v36
	v_pk_add_f32 v[4:5], v[4:5], v[52:53]
	v_lshlrev_b32_e32 v52, 16, v37
	v_and_b32_e32 v53, 0xffff0000, v37
	v_pk_add_f32 v[6:7], v[6:7], v[52:53]
	s_waitcnt vmcnt(6)
	v_lshlrev_b32_e32 v52, 16, v38
	v_and_b32_e32 v53, 0xffff0000, v38
	v_pk_add_f32 v[8:9], v[8:9], v[52:53]
	v_lshlrev_b32_e32 v52, 16, v39
	v_and_b32_e32 v53, 0xffff0000, v39
	v_pk_add_f32 v[10:11], v[10:11], v[52:53]
	s_waitcnt vmcnt(5)
	v_lshlrev_b32_e32 v52, 16, v40
	v_and_b32_e32 v53, 0xffff0000, v40
	v_pk_add_f32 v[16:17], v[16:17], v[52:53]
	v_lshlrev_b32_e32 v52, 16, v41
	v_and_b32_e32 v53, 0xffff0000, v41
	v_pk_add_f32 v[18:19], v[18:19], v[52:53]
	s_waitcnt vmcnt(4)
; __device__ __forceinline__ f32x4 ld_bf4(const bf16* p) { const u32x2 w = *(const u32x2*)p; return (f32x4){__builtin_bit_cast(float, w.x << 16), __builtin_bit_cast(float, w.x & 0xffff0000u), __builtin_bit_cast(float, w.y << 16), __builtin_bit_cast(float, w.y & 0xffff0000u)}; }
; __device__ __forceinline__ void rowwise_phase(const Params& P, int mrows, bool first, int l_post, int j_post, int gate_idx, float coef, bool final_, int l_pre, int j_pre, int shift_idx, int scale_idx) {
;     ...
;                 for (int ks = 1; ks < 8; ++ks) {
; #pragma unroll
;                     for (int j = 0; j < 8; ++j) yv[j] += ld_bf4(pr + (size_t)ks * MCTX * DM + 4 * lane + 256 * j);
;                 }
	v_lshlrev_b32_e32 v52, 16, v42
	v_and_b32_e32 v53, 0xffff0000, v42
	v_pk_add_f32 v[12:13], v[12:13], v[52:53]
	v_lshlrev_b32_e32 v52, 16, v43
	v_and_b32_e32 v53, 0xffff0000, v43
	v_pk_add_f32 v[14:15], v[14:15], v[52:53]
	s_waitcnt vmcnt(3)
	v_lshlrev_b32_e32 v52, 16, v44
	v_and_b32_e32 v53, 0xffff0000, v44
	v_pk_add_f32 v[20:21], v[20:21], v[52:53]
	v_lshlrev_b32_e32 v52, 16, v45
	v_and_b32_e32 v53, 0xffff0000, v45
	v_pk_add_f32 v[22:23], v[22:23], v[52:53]
	s_waitcnt vmcnt(2)
	v_lshlrev_b32_e32 v52, 16, v46
	v_and_b32_e32 v53, 0xffff0000, v46
	v_pk_add_f32 v[24:25], v[24:25], v[52:53]
	v_lshlrev_b32_e32 v52, 16, v47
	v_and_b32_e32 v53, 0xffff0000, v47
	v_pk_add_f32 v[26:27], v[26:27], v[52:53]
	s_waitcnt vmcnt(1)
	v_lshlrev_b32_e32 v52, 16, v48
	v_and_b32_e32 v53, 0xffff0000, v48
	v_pk_add_f32 v[28:29], v[28:29], v[52:53]
	v_lshlrev_b32_e32 v52, 16, v49
	v_and_b32_e32 v53, 0xffff0000, v49
	v_pk_add_f32 v[30:31], v[30:31], v[52:53]
	s_waitcnt vmcnt(0)
	v_lshlrev_b32_e32 v52, 16, v50
	v_and_b32_e32 v53, 0xffff0000, v50
	v_pk_add_f32 v[32:33], v[32:33], v[52:53]
	v_lshlrev_b32_e32 v52, 16, v51
	v_and_b32_e32 v53, 0xffff0000, v51
	v_pk_add_f32 v[34:35], v[34:35], v[52:53]
	s_add_u32 s10, s10, 0x400000
	s_addc_u32 s11, s11, 0
	v_lshlrev_b32_e32 v52, 3, v174
	global_load_dwordx2 v[36:37], v52, s[10:11] offset:0
	global_load_dwordx2 v[38:39], v52, s[10:11] offset:512
	global_load_dwordx2 v[40:41], v52, s[10:11] offset:1024
	global_load_dwordx2 v[42:43], v52, s[10:11] offset:1536
	global_load_dwordx2 v[44:45], v52, s[10:11] offset:2048
	global_load_dwordx2 v[46:47], v52, s[10:11] offset:2560
	global_load_dwordx2 v[48:49], v52, s[10:11] offset:3072
	global_load_dwordx2 v[50:51], v52, s[10:11] offset:3584
	s_waitcnt vmcnt(7)
	v_lshlrev_b32_e32 v52, 16, v36
	v_and_b32_e32 v53, 0xffff0000, v36
	v_pk_add_f32 v[4:5], v[4:5], v[52:53]
	v_lshlrev_b32_e32 v52, 16, v37
	v_and_b32_e32 v53, 0xffff0000, v37
	v_pk_add_f32 v[6:7], v[6:7], v[52:53]
	s_waitcnt vmcnt(6)
	v_lshlrev_b32_e32 v52, 16, v38
	v_and_b32_e32 v53, 0xffff0000, v38
	v_pk_add_f32 v[8:9], v[8:9], v[52:53]
	v_lshlrev_b32_e32 v52, 16, v39
	v_and_b32_e32 v53, 0xffff0000, v39
	v_pk_add_f32 v[10:11], v[10:11], v[52:53]
	s_waitcnt vmcnt(5)
	v_lshlrev_b32_e32 v52, 16, v40
	v_and_b32_e32 v53, 0xffff0000, v40
	v_pk_add_f32 v[16:17], v[16:17], v[52:53]
	v_lshlrev_b32_e32 v52, 16, v41
	v_and_b32_e32 v53, 0xffff0000, v41
	v_pk_add_f32 v[18:19], v[18:19], v[52:53]
	s_waitcnt vmcnt(4)
	v_lshlrev_b32_e32 v52, 16, v42
	v_and_b32_e32 v53, 0xffff0000, v42
	v_pk_add_f32 v[12:13], v[12:13], v[52:53]
	v_lshlrev_b32_e32 v52, 16, v43
	v_and_b32_e32 v53, 0xffff0000, v43
	v_pk_add_f32 v[14:15], v[14:15], v[52:53]
	s_waitcnt vmcnt(3)
	v_lshlrev_b32_e32 v52, 16, v44
	v_and_b32_e32 v53, 0xffff0000, v44
	v_pk_add_f32 v[20:21], v[20:21], v[52:53]
	v_lshlrev_b32_e32 v52, 16, v45
	v_and_b32_e32 v53, 0xffff0000, v45
	v_pk_add_f32 v[22:23], v[22:23], v[52:53]
	s_waitcnt vmcnt(2)
	v_lshlrev_b32_e32 v52, 16, v46
	v_and_b32_e32 v53, 0xffff0000, v46
	v_pk_add_f32 v[24:25], v[24:25], v[52:53]
	v_lshlrev_b32_e32 v52, 16, v47
	v_and_b32_e32 v53, 0xffff0000, v47
	v_pk_add_f32 v[26:27], v[26:27], v[52:53]
	s_waitcnt vmcnt(1)
	v_lshlrev_b32_e32 v52, 16, v48
	v_and_b32_e32 v53, 0xffff0000, v48
	v_pk_add_f32 v[28:29], v[28:29], v[52:53]
	v_lshlrev_b32_e32 v52, 16, v49
	v_and_b32_e32 v53, 0xffff0000, v49
	v_pk_add_f32 v[30:31], v[30:31], v[52:53]
	s_waitcnt vmcnt(0)
	v_lshlrev_b32_e32 v52, 16, v50
	v_and_b32_e32 v53, 0xffff0000, v50
	v_pk_add_f32 v[32:33], v[32:33], v[52:53]
	v_lshlrev_b32_e32 v52, 16, v51
	v_and_b32_e32 v53, 0xffff0000, v51
	v_pk_add_f32 v[34:35], v[34:35], v[52:53]
	s_add_u32 s10, s10, 0x400000
	s_addc_u32 s11, s11, 0
	v_lshlrev_b32_e32 v52, 3, v174
	global_load_dwordx2 v[36:37], v52, s[10:11] offset:0
	global_load_dwordx2 v[38:39], v52, s[10:11] offset:512
	global_load_dwordx2 v[40:41], v52, s[10:11] offset:1024
	global_load_dwordx2 v[42:43], v52, s[10:11] offset:1536
	global_load_dwordx2 v[44:45], v52, s[10:11] offset:2048
	global_load_dwordx2 v[46:47], v52, s[10:11] offset:2560
	global_load_dwordx2 v[48:49], v52, s[10:11] offset:3072
	global_load_dwordx2 v[50:51], v52, s[10:11] offset:3584
	s_waitcnt vmcnt(7)
	v_lshlrev_b32_e32 v52, 16, v36
	v_and_b32_e32 v53, 0xffff0000, v36
	v_pk_add_f32 v[4:5], v[4:5], v[52:53]
	v_lshlrev_b32_e32 v52, 16, v37
	v_and_b32_e32 v53, 0xffff0000, v37
	v_pk_add_f32 v[6:7], v[6:7], v[52:53]
	s_waitcnt vmcnt(6)
	v_lshlrev_b32_e32 v52, 16, v38
	v_and_b32_e32 v53, 0xffff0000, v38
	v_pk_add_f32 v[8:9], v[8:9], v[52:53]
	v_lshlrev_b32_e32 v52, 16, v39
	v_and_b32_e32 v53, 0xffff0000, v39
	v_pk_add_f32 v[10:11], v[10:11], v[52:53]
	s_waitcnt vmcnt(5)
	v_lshlrev_b32_e32 v52, 16, v40
	v_and_b32_e32 v53, 0xffff0000, v40
	v_pk_add_f32 v[16:17], v[16:17], v[52:53]
	v_lshlrev_b32_e32 v52, 16, v41
	v_and_b32_e32 v53, 0xffff0000, v41
	v_pk_add_f32 v[18:19], v[18:19], v[52:53]
	s_waitcnt vmcnt(4)
	v_lshlrev_b32_e32 v52, 16, v42
	v_and_b32_e32 v53, 0xffff0000, v42
	v_pk_add_f32 v[12:13], v[12:13], v[52:53]
	v_lshlrev_b32_e32 v52, 16, v43
	v_and_b32_e32 v53, 0xffff0000, v43
	v_pk_add_f32 v[14:15], v[14:15], v[52:53]
	s_waitcnt vmcnt(3)
	v_lshlrev_b32_e32 v52, 16, v44
	v_and_b32_e32 v53, 0xffff0000, v44
	v_pk_add_f32 v[20:21], v[20:21], v[52:53]
	v_lshlrev_b32_e32 v52, 16, v45
	v_and_b32_e32 v53, 0xffff0000, v45
	v_pk_add_f32 v[22:23], v[22:23], v[52:53]
	s_waitcnt vmcnt(2)
	v_lshlrev_b32_e32 v52, 16, v46
	v_and_b32_e32 v53, 0xffff0000, v46
	v_pk_add_f32 v[24:25], v[24:25], v[52:53]
	v_lshlrev_b32_e32 v52, 16, v47
	v_and_b32_e32 v53, 0xffff0000, v47
	v_pk_add_f32 v[26:27], v[26:27], v[52:53]
	s_waitcnt vmcnt(1)
; __device__ __forceinline__ f32x4 ld_bf4(const bf16* p) { const u32x2 w = *(const u32x2*)p; return (f32x4){__builtin_bit_cast(float, w.x << 16), __builtin_bit_cast(float, w.x & 0xffff0000u), __builtin_bit_cast(float, w.y << 16), __builtin_bit_cast(float, w.y & 0xffff0000u)}; }
; __device__ __forceinline__ void rowwise_phase(const Params& P, int mrows, bool first, int l_post, int j_post, int gate_idx, float coef, bool final_, int l_pre, int j_pre, int shift_idx, int scale_idx) {
;     ...
;                 for (int ks = 1; ks < 8; ++ks) {
; #pragma unroll
;                     for (int j = 0; j < 8; ++j) yv[j] += ld_bf4(pr + (size_t)ks * MCTX * DM + 4 * lane + 256 * j);
;                 }
	v_lshlrev_b32_e32 v52, 16, v48
	v_and_b32_e32 v53, 0xffff0000, v48
	v_pk_add_f32 v[28:29], v[28:29], v[52:53]
	v_lshlrev_b32_e32 v52, 16, v49
	v_and_b32_e32 v53, 0xffff0000, v49
	v_pk_add_f32 v[30:31], v[30:31], v[52:53]
	s_waitcnt vmcnt(0)
	v_lshlrev_b32_e32 v52, 16, v50
	v_and_b32_e32 v53, 0xffff0000, v50
	v_pk_add_f32 v[32:33], v[32:33], v[52:53]
	v_lshlrev_b32_e32 v52, 16, v51
	v_and_b32_e32 v53, 0xffff0000, v51
	v_pk_add_f32 v[34:35], v[34:35], v[52:53]
	s_add_u32 s10, s10, 0x400000
	s_addc_u32 s11, s11, 0
	v_lshlrev_b32_e32 v52, 3, v174
	global_load_dwordx2 v[36:37], v52, s[10:11] offset:0
	global_load_dwordx2 v[38:39], v52, s[10:11] offset:512
	global_load_dwordx2 v[40:41], v52, s[10:11] offset:1024
	global_load_dwordx2 v[42:43], v52, s[10:11] offset:1536
	global_load_dwordx2 v[44:45], v52, s[10:11] offset:2048
	global_load_dwordx2 v[46:47], v52, s[10:11] offset:2560
	global_load_dwordx2 v[48:49], v52, s[10:11] offset:3072
	global_load_dwordx2 v[50:51], v52, s[10:11] offset:3584
	s_waitcnt vmcnt(7)
	v_lshlrev_b32_e32 v52, 16, v36
	v_and_b32_e32 v53, 0xffff0000, v36
	v_pk_add_f32 v[4:5], v[4:5], v[52:53]
	v_lshlrev_b32_e32 v52, 16, v37
	v_and_b32_e32 v53, 0xffff0000, v37
	v_pk_add_f32 v[6:7], v[6:7], v[52:53]
	s_waitcnt vmcnt(6)
	v_lshlrev_b32_e32 v52, 16, v38
	v_and_b32_e32 v53, 0xffff0000, v38
	v_pk_add_f32 v[8:9], v[8:9], v[52:53]
	v_lshlrev_b32_e32 v52, 16, v39
	v_and_b32_e32 v53, 0xffff0000, v39
	v_pk_add_f32 v[10:11], v[10:11], v[52:53]
	s_waitcnt vmcnt(5)
	v_lshlrev_b32_e32 v52, 16, v40
	v_and_b32_e32 v53, 0xffff0000, v40
	v_pk_add_f32 v[16:17], v[16:17], v[52:53]
	v_lshlrev_b32_e32 v52, 16, v41
	v_and_b32_e32 v53, 0xffff0000, v41
	v_pk_add_f32 v[18:19], v[18:19], v[52:53]
	s_waitcnt vmcnt(4)
	v_lshlrev_b32_e32 v52, 16, v42
	v_and_b32_e32 v53, 0xffff0000, v42
	v_pk_add_f32 v[12:13], v[12:13], v[52:53]
	v_lshlrev_b32_e32 v52, 16, v43
	v_and_b32_e32 v53, 0xffff0000, v43
	v_pk_add_f32 v[14:15], v[14:15], v[52:53]
	s_waitcnt vmcnt(3)
	v_lshlrev_b32_e32 v52, 16, v44
	v_and_b32_e32 v53, 0xffff0000, v44
	v_pk_add_f32 v[20:21], v[20:21], v[52:53]
	v_lshlrev_b32_e32 v52, 16, v45
	v_and_b32_e32 v53, 0xffff0000, v45
	v_pk_add_f32 v[22:23], v[22:23], v[52:53]
	s_waitcnt vmcnt(2)
	v_lshlrev_b32_e32 v52, 16, v46
	v_and_b32_e32 v53, 0xffff0000, v46
	v_pk_add_f32 v[24:25], v[24:25], v[52:53]
	v_lshlrev_b32_e32 v52, 16, v47
	v_and_b32_e32 v53, 0xffff0000, v47
	v_pk_add_f32 v[26:27], v[26:27], v[52:53]
	s_waitcnt vmcnt(1)
	v_lshlrev_b32_e32 v52, 16, v48
	v_and_b32_e32 v53, 0xffff0000, v48
	v_pk_add_f32 v[28:29], v[28:29], v[52:53]
	v_lshlrev_b32_e32 v52, 16, v49
	v_and_b32_e32 v53, 0xffff0000, v49
	v_pk_add_f32 v[30:31], v[30:31], v[52:53]
	s_waitcnt vmcnt(0)
	v_lshlrev_b32_e32 v52, 16, v50
	v_and_b32_e32 v53, 0xffff0000, v50
	v_pk_add_f32 v[32:33], v[32:33], v[52:53]
	v_lshlrev_b32_e32 v52, 16, v51
	v_and_b32_e32 v53, 0xffff0000, v51
	v_pk_add_f32 v[34:35], v[34:35], v[52:53]
	s_add_u32 s10, s10, 0x400000
	s_addc_u32 s11, s11, 0
	v_lshlrev_b32_e32 v52, 3, v174
	global_load_dwordx2 v[36:37], v52, s[10:11] offset:0
	global_load_dwordx2 v[38:39], v52, s[10:11] offset:512
	global_load_dwordx2 v[40:41], v52, s[10:11] offset:1024
	global_load_dwordx2 v[42:43], v52, s[10:11] offset:1536
	global_load_dwordx2 v[44:45], v52, s[10:11] offset:2048
	global_load_dwordx2 v[46:47], v52, s[10:11] offset:2560
	global_load_dwordx2 v[48:49], v52, s[10:11] offset:3072
	global_load_dwordx2 v[50:51], v52, s[10:11] offset:3584
	s_waitcnt vmcnt(7)
	v_lshlrev_b32_e32 v52, 16, v36
	v_and_b32_e32 v53, 0xffff0000, v36
	v_pk_add_f32 v[4:5], v[4:5], v[52:53]
	v_lshlrev_b32_e32 v52, 16, v37
	v_and_b32_e32 v53, 0xffff0000, v37
	v_pk_add_f32 v[6:7], v[6:7], v[52:53]
	s_waitcnt vmcnt(6)
	v_lshlrev_b32_e32 v52, 16, v38
	v_and_b32_e32 v53, 0xffff0000, v38
	v_pk_add_f32 v[8:9], v[8:9], v[52:53]
	v_lshlrev_b32_e32 v52, 16, v39
	v_and_b32_e32 v53, 0xffff0000, v39
	v_pk_add_f32 v[10:11], v[10:11], v[52:53]
	s_waitcnt vmcnt(5)
; __device__ __forceinline__ f32x4 ld_bf4(const bf16* p) { const u32x2 w = *(const u32x2*)p; return (f32x4){__builtin_bit_cast(float, w.x << 16), __builtin_bit_cast(float, w.x & 0xffff0000u), __builtin_bit_cast(float, w.y << 16), __builtin_bit_cast(float, w.y & 0xffff0000u)}; }
; __device__ __forceinline__ void rowwise_phase(const Params& P, int mrows, bool first, int l_post, int j_post, int gate_idx, float coef, bool final_, int l_pre, int j_pre, int shift_idx, int scale_idx) {
;     ...
;                 for (int ks = 1; ks < 8; ++ks) {
; #pragma unroll
;                     for (int j = 0; j < 8; ++j) yv[j] += ld_bf4(pr + (size_t)ks * MCTX * DM + 4 * lane + 256 * j);
;                 }
	v_lshlrev_b32_e32 v52, 16, v40
	v_and_b32_e32 v53, 0xffff0000, v40
	v_pk_add_f32 v[16:17], v[16:17], v[52:53]
	v_lshlrev_b32_e32 v52, 16, v41
	v_and_b32_e32 v53, 0xffff0000, v41
	v_pk_add_f32 v[18:19], v[18:19], v[52:53]
	s_waitcnt vmcnt(4)
	v_lshlrev_b32_e32 v52, 16, v42
	v_and_b32_e32 v53, 0xffff0000, v42
	v_pk_add_f32 v[12:13], v[12:13], v[52:53]
	v_lshlrev_b32_e32 v52, 16, v43
	v_and_b32_e32 v53, 0xffff0000, v43
	v_pk_add_f32 v[14:15], v[14:15], v[52:53]
	s_waitcnt vmcnt(3)
	v_lshlrev_b32_e32 v52, 16, v44
	v_and_b32_e32 v53, 0xffff0000, v44
	v_pk_add_f32 v[20:21], v[20:21], v[52:53]
	v_lshlrev_b32_e32 v52, 16, v45
	v_and_b32_e32 v53, 0xffff0000, v45
	v_pk_add_f32 v[22:23], v[22:23], v[52:53]
	s_waitcnt vmcnt(2)
	v_lshlrev_b32_e32 v52, 16, v46
	v_and_b32_e32 v53, 0xffff0000, v46
	v_pk_add_f32 v[24:25], v[24:25], v[52:53]
	v_lshlrev_b32_e32 v52, 16, v47
	v_and_b32_e32 v53, 0xffff0000, v47
	v_pk_add_f32 v[26:27], v[26:27], v[52:53]
	s_waitcnt vmcnt(1)
	v_lshlrev_b32_e32 v52, 16, v48
	v_and_b32_e32 v53, 0xffff0000, v48
	v_pk_add_f32 v[28:29], v[28:29], v[52:53]
	v_lshlrev_b32_e32 v52, 16, v49
	v_and_b32_e32 v53, 0xffff0000, v49
	v_pk_add_f32 v[30:31], v[30:31], v[52:53]
	s_waitcnt vmcnt(0)
	v_lshlrev_b32_e32 v52, 16, v50
	v_and_b32_e32 v53, 0xffff0000, v50
	v_pk_add_f32 v[32:33], v[32:33], v[52:53]
	v_lshlrev_b32_e32 v52, 16, v51
	v_and_b32_e32 v53, 0xffff0000, v51
	v_pk_add_f32 v[34:35], v[34:35], v[52:53]
	s_add_u32 s10, s10, 0x400000
	s_addc_u32 s11, s11, 0
	v_lshlrev_b32_e32 v52, 3, v174
	global_load_dwordx2 v[36:37], v52, s[10:11] offset:0
	global_load_dwordx2 v[38:39], v52, s[10:11] offset:512
	global_load_dwordx2 v[40:41], v52, s[10:11] offset:1024
	global_load_dwordx2 v[42:43], v52, s[10:11] offset:1536
	global_load_dwordx2 v[44:45], v52, s[10:11] offset:2048
	global_load_dwordx2 v[46:47], v52, s[10:11] offset:2560
	global_load_dwordx2 v[48:49], v52, s[10:11] offset:3072
	global_load_dwordx2 v[50:51], v52, s[10:11] offset:3584
	s_waitcnt vmcnt(7)
	v_lshlrev_b32_e32 v52, 16, v36
	v_and_b32_e32 v53, 0xffff0000, v36
	v_pk_add_f32 v[4:5], v[4:5], v[52:53]
	v_lshlrev_b32_e32 v52, 16, v37
	v_and_b32_e32 v53, 0xffff0000, v37
	v_pk_add_f32 v[6:7], v[6:7], v[52:53]
	s_waitcnt vmcnt(6)
	v_lshlrev_b32_e32 v52, 16, v38
	v_and_b32_e32 v53, 0xffff0000, v38
	v_pk_add_f32 v[8:9], v[8:9], v[52:53]
	v_lshlrev_b32_e32 v52, 16, v39
	v_and_b32_e32 v53, 0xffff0000, v39
	v_pk_add_f32 v[10:11], v[10:11], v[52:53]
	s_waitcnt vmcnt(5)
	v_lshlrev_b32_e32 v52, 16, v40
	v_and_b32_e32 v53, 0xffff0000, v40
	v_pk_add_f32 v[16:17], v[16:17], v[52:53]
	v_lshlrev_b32_e32 v52, 16, v41
	v_and_b32_e32 v53, 0xffff0000, v41
	v_pk_add_f32 v[18:19], v[18:19], v[52:53]
	s_waitcnt vmcnt(4)
	v_lshlrev_b32_e32 v52, 16, v42
	v_and_b32_e32 v53, 0xffff0000, v42
	v_pk_add_f32 v[12:13], v[12:13], v[52:53]
	v_lshlrev_b32_e32 v52, 16, v43
	v_and_b32_e32 v53, 0xffff0000, v43
	v_pk_add_f32 v[14:15], v[14:15], v[52:53]
	s_waitcnt vmcnt(3)
	v_lshlrev_b32_e32 v52, 16, v44
	v_and_b32_e32 v53, 0xffff0000, v44
	v_pk_add_f32 v[20:21], v[20:21], v[52:53]
	v_lshlrev_b32_e32 v52, 16, v45
	v_and_b32_e32 v53, 0xffff0000, v45
	v_pk_add_f32 v[22:23], v[22:23], v[52:53]
	s_waitcnt vmcnt(2)
	v_lshlrev_b32_e32 v52, 16, v46
	v_and_b32_e32 v53, 0xffff0000, v46
	v_pk_add_f32 v[24:25], v[24:25], v[52:53]
	v_lshlrev_b32_e32 v52, 16, v47
	v_and_b32_e32 v53, 0xffff0000, v47
	v_pk_add_f32 v[26:27], v[26:27], v[52:53]
	s_waitcnt vmcnt(1)
	v_lshlrev_b32_e32 v52, 16, v48
	v_and_b32_e32 v53, 0xffff0000, v48
	v_pk_add_f32 v[28:29], v[28:29], v[52:53]
	v_lshlrev_b32_e32 v52, 16, v49
	v_and_b32_e32 v53, 0xffff0000, v49
	v_pk_add_f32 v[30:31], v[30:31], v[52:53]
	s_waitcnt vmcnt(0)
	v_lshlrev_b32_e32 v52, 16, v50
	v_and_b32_e32 v53, 0xffff0000, v50
	v_pk_add_f32 v[32:33], v[32:33], v[52:53]
	v_lshlrev_b32_e32 v52, 16, v51
	v_and_b32_e32 v53, 0xffff0000, v51
	v_pk_add_f32 v[34:35], v[34:35], v[52:53]
	s_mov_b64 s[10:11], 0

; __device__ __forceinline__ unsigned cvtpk(float lo, float hi) { f32x2 v = {lo, hi}; bf16x2_n b = __builtin_convertvector(v, bf16x2_n); return __builtin_bit_cast(unsigned, b); }
; __device__ __forceinline__ void scan_ret_mfma(const Params& P, unsigned char* LB, int c) {
;     ...
;         for (int ch = 0; ch < 2; ++ch) {
;             const f32x4 y = chunk_step<64, 64>(OP + ch * ChunkLds<64, 64>::SIZE, wave * 16, fr, fq, S);
;             const int row = scan_row(b, d, tile * 32 + ch * 16 + fr);
;             { u32x2 w_; w_.x = cvtpk(y[0], y[1]); w_.y = cvtpk(y[2], y[3]); *(u32x2*)(YD + ((size_t)(3 * 2 + d) * MALL + row) * 512 + h * 128 + vh * 64 + wave * 16 + 4 * fq) = w_; }
;         }
.LBB0_90:
	v_ashrrev_i32_e32 v1, 31, v0
	v_lshl_add_u64 v[0:1], v[0:1], 0, s[22:23]
	s_nop 1
	v_pk_add_f32 v[34:35], v[34:35], v[38:39]
	v_pk_add_f32 v[32:33], v[32:33], v[36:37]
	v_lshlrev_b64 v[0:1], 10, v[0:1]
	v_cvt_pk_bf16_f32 v32, v32, v33
	v_cvt_pk_bf16_f32 v33, v34, v35
	v_lshl_add_u64 v[0:1], v[50:51], 0, v[0:1]
	global_store_dwordx2 v[0:1], v[32:33], off
	s_waitcnt vmcnt(2)
	s_branch .Lret_unpack

; #define RETM_LOAD(tile) do { const bf16* ur_ = (const bf16*)(P.ws + WS_UG) + (size_t)scan_row(b, d, (tile) * 32 + st) * NUG; r1 = ld_bf4(ur_ + qkbase); r2 = ld_bf4(ur_ + qkbase + 16); \
;         rv0 = ld_bf4((const bf16*)(P.ws + WS_UG) + (size_t)scan_row(b, d, (tile) * 32 + st) * NUG + G_RT_V + h * 128 + vh * 64 + rem * 4); } while (0)
; __device__ __forceinline__ void scan_ret_mfma(const Params& P, unsigned char* LB, int c) {
;     ...
;     RETM_LOAD(0);
;     for (int tile = 0; tile < NTILES; ++tile) {
.Lret_unpack:
	v_lshlrev_b32_e32 v4, 16, v6
	v_and_b32_e32 v5, 0xffff0000, v6
	v_lshlrev_b32_e32 v6, 16, v7
	v_and_b32_e32 v7, 0xffff0000, v7
	v_lshlrev_b32_e32 v8, 16, v10
	v_and_b32_e32 v9, 0xffff0000, v10
	v_lshlrev_b32_e32 v10, 16, v11
	v_and_b32_e32 v11, 0xffff0000, v11
	v_lshlrev_b32_e32 v12, 16, v14
	v_and_b32_e32 v13, 0xffff0000, v14
	v_lshlrev_b32_e32 v14, 16, v15
	v_and_b32_e32 v15, 0xffff0000, v15
	s_cmpk_eq_i32 s37, 0x48
	s_mov_b32 s36, s37
	s_cbranch_scc1 .LBB0_115

; #define RETM_LOAD(tile) do { const bf16* ur_ = (const bf16*)(P.ws + WS_UG) + (size_t)scan_row(b, d, (tile) * 32 + st) * NUG; r1 = ld_bf4(ur_ + qkbase); r2 = ld_bf4(ur_ + qkbase + 16); \
;         rv0 = ld_bf4((const bf16*)(P.ws + WS_UG) + (size_t)scan_row(b, d, (tile) * 32 + st) * NUG + G_RT_V + h * 128 + vh * 64 + rem * 4); } while (0)
; __device__ __forceinline__ void scan_ret_mfma(const Params& P, unsigned char* LB, int c) {
;     ...
;         { f32x4 o1 = r1, o2 = r2;
;           if (tile >= TC / 32) {
;               const int tok = scan_row(b, d, tile * 32 + st) & (TL - 1); const int pos = hs ? (tok & 63) : (tok >> 6);
;               const f32x4 cs0 = *(const f32x4*)&rope[(pos * 16 + 4 * cc) * 2], cs1 = *(const f32x4*)&rope[(pos * 16 + 4 * cc) * 2 + 4];
;               const f32x4 cv = {cs0.x, cs0.z, cs1.x, cs1.z}, sv = {cs0.y, cs0.w, cs1.y, cs1.w};
;               o1 = r1 * cv - r2 * sv; o2 = r1 * sv + r2 * cv;
;           }
;           float* dst = isk ? rk : rq; const float scl = isk ? 0.125f : 1.f;
;           *(f32x4*)&dst[st * 64 + hs * 32 + 4 * cc] = o1 * scl; *(f32x4*)&dst[st * 64 + hs * 32 + 16 + 4 * cc] = o2 * scl;
;           *(f32x4*)&rv[st * 64 + rem * 4] = rv0; }
;         __syncthreads();
;         if (tile + 1 < NTILES) RETM_LOAD(tile + 1);
.LBB0_94:
	v_pk_mul_f32 v[34:35], v[48:49], v[34:35]
	v_pk_mul_f32 v[32:33], v[44:45], v[32:33]
	s_add_i32 s37, s36, 1
	ds_write_b128 v66, v[32:35]
	v_pk_mul_f32 v[34:35], v[48:49], v[38:39]
	v_pk_mul_f32 v[32:33], v[44:45], v[36:37]
	s_cmpk_eq_i32 s36, 0x47
	ds_write_b128 v66, v[32:35] offset:64
	ds_write_b128 v63, v[12:15] offset:49152
	s_waitcnt lgkmcnt(0)
	s_barrier
	s_cbranch_scc1 .LBB0_96
	v_lshl_add_u32 v0, s37, 5, v58
	s_movk_i32 s2, 0x100
	v_cmp_gt_i32_e32 vcc, s2, v0
	v_add_u32_e32 v1, 0xffffff00, v0
	s_movk_i32 s2, 0x2a00
	v_cndmask_b32_e32 v2, v185, v186, vcc
	v_cndmask_b32_e32 v1, v1, v0, vcc
	v_sub_u32_e32 v0, v2, v0
	v_cndmask_b32_e32 v4, v61, v60, vcc
	v_cndmask_b32_e64 v0, v0, v1, s[20:21]
	v_add_u32_e32 v2, v0, v4
	v_mov_b64_e32 v[4:5], s[94:95]
	v_mad_i64_i32 v[4:5], s[28:29], v2, s2, v[4:5]
	v_lshl_add_u64 v[4:5], v[4:5], 0, s[58:59]
	s_mov_b32 s27, s59
	v_lshl_add_u64 v[4:5], v[4:5], 0, s[26:27]
	v_mov_b32_e32 v55, v3
	v_lshl_add_u64 v[4:5], v[4:5], 0, v[54:55]
	v_add_co_u32_e32 v4, vcc, 0x26201000, v4
	v_mad_i64_i32 v[0:1], s[28:29], v2, s2, v[52:53]
	s_nop 0
	v_addc_co_u32_e32 v5, vcc, 0, v5, vcc
	global_load_dwordx2 v[6:7], v[0:1], off
	s_nop 0
	global_load_dwordx2 v[10:11], v[0:1], off offset:32
	s_movk_i32 s91, 0x2a00
	global_load_dwordx2 v[14:15], v[4:5], off offset:1024

; __device__ __forceinline__ int tid_() { int t = threadIdx.x; asm volatile("" : "+v"(t)); return t; }
; __device__ __forceinline__ unsigned cvtpk(float lo, float hi) { f32x2 v = {lo, hi}; bf16x2_n b = __builtin_convertvector(v, bf16x2_n); return __builtin_bit_cast(unsigned, b); }
; #define SSM_LOAD(tile) do { const int row_ = scan_row(b, d, (tile) * 32 + st); const bf16* xr_ = XBC + (size_t)row_ * 768; \
;         px = ld_bf4(xr_ + h * 64 + sc4); pB = ld_bf4(xr_ + 512 + g * 64 + sc4); pC = ld_bf4(xr_ + 640 + g * 64 + sc4); pdt = U[(size_t)row_ * NUF + U_SSD_DT + d * 8 + h]; } while (0)
; __device__ __forceinline__ void scan_ssd_mfma(const Params& P, unsigned char* LB, int l, int c) {
;     const int tid = tid_(), lane = tid & 63, wave = __builtin_amdgcn_readfirstlane(tid >> 6), fr = lane & 15, fq = lane >> 4;
;     const int b = c >> 4, d = (c >> 3) & 1, h = c & 7, g = h >> 2;
;     const float* U = (const float*)(P.ws + WS_U); const bf16* XBC = (const bf16*)(P.ws + WS_XBC); bf16* YD = (bf16*)(P.ws + WS_YD);
;     float* rq = (float*)(LB + L_RAW_Q); float* rk = (float*)(LB + L_RAW_K); float* rL = (float*)(LB + L_RAW_L); float* lg = (float*)(LB + L_RAW_L + 256); float* rv = (float*)(LB + L_RAW_V);
;     unsigned char* OP = LB + L_OP;
;     const float dtb = P.ssd_dt_bias[(l * 2 + d) * 8 + h], aneg = -__expf(P.ssd_a_log[(l * 2 + d) * 8 + h]);
;     const int st = tid >> 4, sc4 = (tid & 15) << 2;
;     __syncthreads();
;     zero_operand_pads<64, 64>(OP, tid, 512);
;     f32x4 S[4];
; #pragma unroll
;     for (int i = 0; i < 4; ++i) S[i] = (f32x4){0.f, 0.f, 0.f, 0.f};
;     f32x4 px, pB, pC; float pdt;
;     ...
;     SSM_LOAD(0);
;     ...
;             for (int ch = 0; ch < 2; ++ch) {
;                 const f32x4 y = chunk_step<64, 64>(OP + ch * ChunkLds<64, 64>::SIZE, wave * 16, fr, fq, S);
;                 const int row = scan_row(b, d, tile * 32 + ch * 16 + fr);
;                 { u32x2 w_; w_.x = cvtpk(y[0], y[1]); w_.y = cvtpk(y[2], y[3]); *(u32x2*)(YD + ((size_t)(0 * 2 + d) * MALL + row) * 512 + h * 64 + wave * 16 + 4 * fq) = w_; }
.LBB0_124:
	s_or_b64 exec, exec, s[8:9]
	v_readlane_b32 s2, v255, 30
	v_readlane_b32 s3, v255, 31
	v_and_b32_e32 v56, 15, v50
	s_lshl_b32 s58, s12, 7
	v_mov_b64_e32 v[4:5], s[2:3]
	s_movk_i32 s2, 0x600
	v_mad_i64_i32 v[4:5], s[8:9], v0, s2, v[4:5]
	s_lshl_b32 s8, s10, 4
	s_and_b32 s62, s8, 64
	s_lshl_b32 s8, s62, 1
	s_mov_b32 s9, s59
	v_lshl_add_u64 v[6:7], v[4:5], 0, s[58:59]
	v_lshlrev_b32_e32 v2, 3, v56
	v_lshl_add_u64 v[4:5], v[4:5], 0, s[8:9]
	v_readlane_b32 s28, v255, 35
	v_lshl_add_u64 v[6:7], v[6:7], 0, v[2:3]
	v_lshl_add_u64 v[4:5], v[4:5], 0, v[2:3]
	v_readlane_b32 s29, v255, 36
	global_load_dwordx2 v[6:7], v[6:7], off
	s_nop 0
	global_load_dwordx2 v[8:9], v[4:5], off offset:1024
	global_load_dwordx2 v[10:11], v[4:5], off offset:1280
	v_mov_b64_e32 v[4:5], s[28:29]
	s_lshl_b32 s63, s12, 6
	s_lshl_b32 s18, s13, 2
	s_mov_b32 s19, s59
	s_lshl_b32 s24, s12, 2
	v_mad_i64_i32 v[0:1], s[12:13], v0, s76, v[4:5]
	s_mov_b32 s25, s59
	v_lshl_add_u64 v[0:1], v[0:1], 0, s[18:19]
	v_lshl_add_u64 v[0:1], v[0:1], 0, s[24:25]
	global_load_dword v49, v[0:1], off
	s_ashr_i32 s26, s14, 6
	s_add_u32 s23, s28, s18
	v_and_b32_e32 v13, 16, v50
	s_addc_u32 s25, s29, 0
	s_add_u32 s96, s23, s24
	v_or_b32_e32 v1, 2, v13
	s_addc_u32 s97, s25, 0
	v_cmp_gt_i32_e64 s[28:29], v1, v50
	v_or_b32_e32 v1, 3, v13
	s_cmp_lt_i32 s26, 4
	v_cmp_gt_i32_e64 s[30:31], v1, v50
	v_or_b32_e32 v1, 4, v13
	s_movk_i32 s2, 0x100
	s_cselect_b64 s[60:61], -1, 0
	s_cmp_eq_u32 s22, 0
	v_cmp_gt_i32_e64 s[34:35], v1, v50
	v_or_b32_e32 v1, 5, v13
	v_cmp_gt_i32_e64 s[10:11], s2, v50
	s_mul_i32 s92, s22, 0x2400
	s_cselect_b64 s[22:23], -1, 0
	s_lshl_b32 s24, s26, 4
	v_readlane_b32 s2, v255, 32
	v_cmp_gt_i32_e64 s[36:37], v1, v50
	v_or_b32_e32 v1, 6, v13
	s_add_u32 s26, s2, s58
	v_readlane_b32 s3, v255, 33
	v_cmp_gt_i32_e64 s[38:39], v1, v50
	v_or_b32_e32 v1, 7, v13
	v_bfe_u32 v12, v50, 4, 2
	s_addc_u32 s27, s3, 0
	s_ashr_i32 s25, s24, 31
	v_cmp_gt_i32_e64 s[40:41], v1, v50
	v_or_b32_e32 v1, 8, v13
	v_lshlrev_b32_e32 v5, 2, v12
	v_or_b32_e32 v0, s24, v56
	s_lshl_b64 s[24:25], s[24:25], 1
	v_cmp_gt_i32_e64 s[42:43], v1, v50
	v_or_b32_e32 v1, 9, v13
	v_or_b32_e32 v14, 2, v5
	s_add_u32 s24, s26, s24
	v_cmp_gt_i32_e64 s[44:45], v1, v50
	v_or_b32_e32 v1, 10, v13
	v_readlane_b32 s58, v254, 6
	v_lshlrev_b32_e32 v60, 4, v12
	v_cmp_gt_u32_e64 s[18:19], v14, v56
	s_addc_u32 s25, s27, s25
	v_cmp_gt_i32_e64 s[46:47], v1, v50
	v_or_b32_e32 v1, 11, v13
	v_mov_b32_e32 v14, s58
	s_add_i32 s58, 0, 0x11b00
	v_cmp_gt_i32_e64 s[48:49], v1, v50
	v_or_b32_e32 v1, 12, v13
	v_add_u32_e32 v15, s58, v60
	v_readlane_b32 s58, v254, 7
	s_movk_i32 s2, 0x50
	v_cmp_gt_i32_e64 s[50:51], v1, v50
	v_or_b32_e32 v1, 13, v13
	v_mov_b32_e32 v16, s58
	v_readlane_b32 s58, v254, 8
	v_mov_b32_e32 v41, v3
	v_lshlrev_b32_e32 v40, 3, v12
	v_mul_lo_u32 v0, v0, s2
	v_cmp_gt_i32_e64 s[52:53], v1, v50
	v_or_b32_e32 v1, 14, v13
	v_readlane_b32 s3, v254, 4
	v_mov_b32_e32 v17, s58
	v_readlane_b32 s58, v254, 9
	v_lshl_add_u64 v[42:43], s[24:25], 0, v[40:41]
	v_lshl_add_u32 v41, v13, 2, 0
	v_cmp_lt_i32_e64 s[26:27], v13, v50
	v_cmp_gt_i32_e64 s[54:55], v1, v50
	v_or_b32_e32 v1, 15, v13
	v_mov_b32_e32 v13, s3
	v_readlane_b32 s3, v254, 5
	v_add_u32_e32 v64, s58, v0
	v_readlane_b32 s58, v254, 10
	v_lshlrev_b32_e32 v4, 4, v56
	v_cmp_gt_i32_e64 s[56:57], v1, v50
	v_mov_b32_e32 v1, s74
	v_add_u32_e32 v63, s3, v0
	v_mov_b32_e32 v0, s58
	v_readlane_b32 s58, v254, 11
	v_lshlrev_b32_e32 v58, 2, v50
	v_lshlrev_b32_e32 v2, 2, v56
	v_mul_u32_u24_e32 v12, 0x50, v56
	v_lshl_or_b32 v4, v53, 8, v4
	v_cmp_gt_u32_e64 s[14:15], v5, v56
	v_cmp_lt_u32_e64 s[16:17], v5, v56
	v_or_b32_e32 v5, 3, v5
	v_mad_u32_u24 v1, v56, s75, v1
	v_mad_u32_u24 v13, v56, s75, v13
	v_mad_u32_u24 v14, v56, s75, v14
	v_mad_u32_u24 v16, v56, s75, v16
	v_mad_u32_u24 v17, v56, s75, v17
	v_mad_u32_u24 v0, v56, s75, v0
	v_add_u32_e32 v18, s58, v60
	v_mul_lo_u32 v19, v50, s2
	v_readlane_b32 s2, v254, 12
	v_mov_b32_e32 v20, 0
	s_mov_b32 s86, 0
	v_cmp_gt_i32_e64 s[8:9], 32, v50
	v_lshl_add_u32 v57, v53, 2, 0
	s_mov_b32 s93, s59
	v_cmp_eq_u32_e64 s[12:13], 0, v56
	v_add_u32_e32 v59, 0, v58
	v_or_b32_e32 v61, 64, v60
	v_add_u32_e32 v62, 0, v4
	v_cmp_gt_u32_e64 s[20:21], v5, v56
	s_waitcnt vmcnt(3)
	v_lshlrev_b32_e32 v4, 16, v6
	v_and_b32_e32 v5, 0xffff0000, v6
	v_lshlrev_b32_e32 v6, 16, v7
	v_and_b32_e32 v7, 0xffff0000, v7
	s_waitcnt vmcnt(2)
	v_lshlrev_b32_e32 v44, 16, v8
	v_and_b32_e32 v45, 0xffff0000, v8
	v_lshlrev_b32_e32 v46, 16, v9
	v_and_b32_e32 v47, 0xffff0000, v9
	s_waitcnt vmcnt(1)
	v_lshlrev_b32_e32 v8, 16, v10
	v_and_b32_e32 v9, 0xffff0000, v10
	v_lshlrev_b32_e32 v10, 16, v11
	v_and_b32_e32 v11, 0xffff0000, v11
	v_cmp_gt_i32_e64 s[24:25], 0, v50
	v_lshl_add_u32 v65, v50, 3, s74
	v_add_u32_e32 v66, 0x11b00, v19
	v_add_u32_e32 v67, s3, v19
	v_add_u32_e32 v68, s2, v58
	s_lshl_b32 s58, s63, 1
	v_lshlrev_b32_e32 v48, 1, v2
	s_lshl_b32 s62, s62, 1
	v_add_u32_e32 v69, v1, v60
	v_add_u32_e32 v70, v13, v60
	v_add_u32_e32 v71, v14, v40
	v_add_u32_e32 v72, v15, v12
	v_add_u32_e32 v73, v16, v60
	v_add_u32_e32 v74, v17, v60
	v_add_u32_e32 v75, v0, v40
	v_add_u32_e32 v76, v18, v12
	v_mov_b32_e32 v21, v20
	v_mov_b32_e32 v22, v20
	v_mov_b32_e32 v23, v20
	v_mov_b32_e32 v24, v20
	v_mov_b32_e32 v25, v20
	v_mov_b32_e32 v26, v20
	v_mov_b32_e32 v27, v20
	v_mov_b32_e32 v16, v20
	v_mov_b32_e32 v17, v20
	v_mov_b32_e32 v18, v20
	v_mov_b32_e32 v19, v20
	v_mov_b32_e32 v12, v20
	v_mov_b32_e32 v13, v20
	v_mov_b32_e32 v14, v20
	v_mov_b32_e32 v15, v20
	s_waitcnt vmcnt(0)
	s_branch .LBB0_127
.LBB0_125:
	v_ashrrev_i32_e32 v1, 31, v0
	v_lshl_add_u64 v[0:1], v[0:1], 0, s[92:93]
	s_nop 1
	v_pk_add_f32 v[30:31], v[30:31], v[34:35]
	v_pk_add_f32 v[28:29], v[28:29], v[32:33]
	v_lshlrev_b64 v[0:1], 10, v[0:1]
	v_cvt_pk_bf16_f32 v28, v28, v29
	v_cvt_pk_bf16_f32 v29, v30, v31
	v_lshl_add_u64 v[0:1], v[42:43], 0, v[0:1]
	global_store_dwordx2 v[0:1], v[28:29], off
	s_waitcnt vmcnt(2)
	s_branch .Lssd_unpack

; __device__ __forceinline__ float softplus_(float x) { return fmaxf(x, 0.f) + log1pf(__expf(-fabsf(x))); }
; #define SSM_LOAD(tile) do { const int row_ = scan_row(b, d, (tile) * 32 + st); const bf16* xr_ = XBC + (size_t)row_ * 768; \
;         px = ld_bf4(xr_ + h * 64 + sc4); pB = ld_bf4(xr_ + 512 + g * 64 + sc4); pC = ld_bf4(xr_ + 640 + g * 64 + sc4); pdt = U[(size_t)row_ * NUF + U_SSD_DT + d * 8 + h]; } while (0)
; __device__ __forceinline__ void scan_ssd_mfma(const Params& P, unsigned char* LB, int l, int c) {
;     ...
;     for (int tile = 0; tile < NTILES; ++tile) {
;         { const float delta = softplus_(pdt + dtb); const int o = st * 64 + sc4;
;           *(f32x4*)&rv[o] = px; *(f32x4*)&rk[o] = pB * delta; *(f32x4*)&rq[o] = pC;
;           if ((tid & 15) == 0) lg[st] = aneg * delta; }
;         __syncthreads();
;         if (tile + 1 < NTILES) SSM_LOAD(tile + 1);
.Lssd_unpack:
	v_lshlrev_b32_e32 v4, 16, v6
	v_and_b32_e32 v5, 0xffff0000, v6
	v_lshlrev_b32_e32 v6, 16, v7
	v_and_b32_e32 v7, 0xffff0000, v7
	v_lshlrev_b32_e32 v44, 16, v8
	v_and_b32_e32 v45, 0xffff0000, v8
	v_lshlrev_b32_e32 v46, 16, v9
	v_and_b32_e32 v47, 0xffff0000, v9
	v_lshlrev_b32_e32 v8, 16, v10
	v_and_b32_e32 v9, 0xffff0000, v10
	v_lshlrev_b32_e32 v10, 16, v11
	v_and_b32_e32 v11, 0xffff0000, v11
	s_cmpk_eq_i32 s90, 0x48
	s_mov_b32 s86, s90
	s_cbranch_scc1 .LBB0_152
.LBB0_127:
	v_add_f32_e32 v0, v51, v49
	s_mov_b32 s2, 0xbfb8aa3b
	v_mul_f32_e64 v1, |v0|, s2
	v_exp_f32_e32 v2, v1
	v_max_f32_e32 v77, 0, v0
	s_mov_b32 s2, 0x3f2aaaab
	ds_write_b128 v62, v[4:7] offset:49152
	v_add_f32_e32 v28, 1.0, v2
	v_add_f32_e32 v0, -1.0, v28
	v_sub_f32_e32 v1, v0, v28
	v_sub_f32_e32 v0, v2, v0
	v_add_f32_e32 v1, 1.0, v1
	v_frexp_mant_f32_e32 v29, v28
	v_add_f32_e32 v30, v0, v1
	v_cvt_f64_f32_e32 v[0:1], v28
	v_frexp_exp_i32_f64_e32 v0, v[0:1]
	v_cmp_gt_f32_e32 vcc, s2, v29
	s_mov_b32 s2, 0x3f317218
	s_nop 0
	v_subbrev_co_u32_e32 v34, vcc, 0, v0, vcc
	v_sub_u32_e32 v0, 0, v34
	v_ldexp_f32 v1, v28, v0
	v_ldexp_f32 v0, v30, v0
	v_add_f32_e32 v28, -1.0, v1
	v_add_f32_e32 v30, 1.0, v1
	v_add_f32_e32 v29, 1.0, v28
	v_add_f32_e32 v31, -1.0, v30
	v_sub_f32_e32 v29, v1, v29
	v_sub_f32_e32 v1, v1, v31
	v_add_f32_e32 v29, v0, v29
	v_add_f32_e32 v0, v0, v1
	v_add_f32_e32 v35, v30, v0
	v_rcp_f32_e32 v37, v35
	v_sub_f32_e32 v1, v35, v30
	v_sub_f32_e32 v36, v0, v1
	v_add_f32_e32 v1, v28, v29
	v_mul_f32_e32 v39, v1, v37
	v_sub_f32_e32 v0, v1, v28
	v_mul_f32_e32 v28, v35, v39
	v_fma_f32 v30, v39, v35, -v28
	v_fmac_f32_e32 v30, v39, v36
	v_sub_f32_e32 v38, v29, v0
	v_add_f32_e32 v0, v28, v30
	v_sub_f32_e32 v29, v1, v0
	v_pk_add_f32 v[32:33], v[0:1], v[28:29] neg_lo:[0,1] neg_hi:[0,1]
	v_mov_b32_e32 v31, v0
	v_pk_add_f32 v[0:1], v[32:33], v[30:31] neg_lo:[0,1] neg_hi:[0,1]
	s_nop 0
	v_add_f32_e32 v1, v38, v1
	v_add_f32_e32 v0, v0, v1
	v_add_f32_e32 v1, v29, v0
	v_mul_f32_e32 v38, v37, v1
	v_mul_f32_e32 v28, v35, v38
	v_fma_f32 v30, v38, v35, -v28
	v_fmac_f32_e32 v30, v38, v36
	v_sub_f32_e32 v29, v29, v1
	v_add_f32_e32 v35, v0, v29
	v_add_f32_e32 v0, v28, v30
	v_sub_f32_e32 v29, v1, v0
	v_pk_add_f32 v[32:33], v[0:1], v[28:29] neg_lo:[0,1] neg_hi:[0,1]
	v_mov_b32_e32 v31, v0
	v_pk_add_f32 v[0:1], v[32:33], v[30:31] neg_lo:[0,1] neg_hi:[0,1]
	s_nop 0
	v_add_f32_e32 v1, v35, v1
	v_add_f32_e32 v0, v0, v1
	v_add_f32_e32 v1, v39, v38
	v_add_f32_e32 v0, v29, v0
	v_sub_f32_e32 v28, v1, v39
	v_mul_f32_e32 v0, v37, v0
	v_sub_f32_e32 v28, v38, v28
	v_add_f32_e32 v28, v28, v0
	v_add_f32_e32 v30, v1, v28
	v_mul_f32_e32 v31, v30, v30
	v_fmamk_f32 v0, v31, 0x3e9b6dac, v170
	v_fmaak_f32 v135, v31, v0, 0x3f2aaada
	v_cvt_f32_i32_e32 v0, v34
	v_sub_f32_e32 v1, v30, v1
	v_sub_f32_e32 v1, v28, v1
	v_ldexp_f32 v32, v1, 1
	v_mul_f32_e32 v1, v30, v31
	v_ldexp_f32 v29, v30, 1
	v_pk_mul_f32 v[30:31], v[0:1], v[134:135]
	s_nop 0
	v_fma_f32 v28, v0, s2, -v30
	v_fmac_f32_e32 v28, 0xb102e308, v0
	v_pk_add_f32 v[0:1], v[30:31], v[28:29]
	s_mov_b32 s2, 0x7f800000
	v_sub_f32_e32 v29, v1, v29
	v_sub_f32_e32 v29, v31, v29
	v_add_f32_e32 v33, v32, v29
	v_mov_b32_e32 v32, v30
	v_pk_add_f32 v[30:31], v[0:1], v[30:31] neg_lo:[0,1] neg_hi:[0,1]
	v_pk_add_f32 v[34:35], v[0:1], v[32:33]
	v_mov_b32_e32 v29, v0
	v_mov_b32_e32 v31, v35
	v_pk_add_f32 v[36:37], v[28:29], v[30:31] neg_lo:[0,1] neg_hi:[0,1]
	v_pk_add_f32 v[28:29], v[28:29], v[30:31]
	v_mov_b32_e32 v32, v33
	v_pk_add_f32 v[30:31], v[28:29], v[0:1] op_sel:[1,0] op_sel_hi:[0,1] neg_lo:[0,1] neg_hi:[0,1]
	v_pk_add_f32 v[38:39], v[34:35], v[30:31] op_sel_hi:[1,0] neg_lo:[0,1] neg_hi:[0,1]
	v_mov_b32_e32 v34, v35
	v_mov_b32_e32 v35, v29
	v_pk_mov_b32 v[30:31], v[0:1], v[30:31] op_sel:[1,0]
	v_mov_b32_e32 v33, v0
	v_pk_add_f32 v[30:31], v[34:35], v[30:31] neg_lo:[0,1] neg_hi:[0,1]
	v_mov_b32_e32 v38, v36
	v_pk_add_f32 v[0:1], v[32:33], v[30:31] neg_lo:[0,1] neg_hi:[0,1]
	v_mov_b32_e32 v37, v29
	v_pk_add_f32 v[30:31], v[38:39], v[0:1]
	v_cmp_neq_f32_e32 vcc, s2, v2
	v_pk_add_f32 v[32:33], v[30:31], v[30:31] op_sel:[0,1] op_sel_hi:[1,0]
	s_mov_b32 s2, 0x33800000
	v_pk_add_f32 v[28:29], v[28:29], v[32:33] op_sel:[1,0] op_sel_hi:[0,1]
	v_mov_b32_e32 v31, v28
	v_pk_add_f32 v[34:35], v[30:31], v[36:37] neg_lo:[0,1] neg_hi:[0,1]
	v_mov_b32_e32 v1, v32
	v_sub_f32_e32 v29, v30, v34
	v_pk_add_f32 v[0:1], v[0:1], v[34:35] neg_lo:[0,1] neg_hi:[0,1]
	v_sub_f32_e32 v29, v36, v29
	v_add_f32_e32 v0, v0, v29
	v_add_f32_e32 v0, v0, v1
	v_add_f32_e32 v0, v28, v0
	v_cndmask_b32_e32 v0, v187, v0, vcc
	v_cmp_ngt_f32_e32 vcc, -1.0, v2
	s_nop 1
	v_cndmask_b32_e32 v0, v188, v0, vcc
	v_cmp_neq_f32_e32 vcc, -1.0, v2
	s_nop 1
	v_cndmask_b32_e32 v0, v189, v0, vcc
	v_cmp_lt_f32_e64 vcc, |v2|, s2
	s_nop 1
	v_cndmask_b32_e32 v0, v0, v2, vcc
	v_add_f32_e32 v0, v77, v0
	v_pk_mul_f32 v[30:31], v[46:47], v[0:1] op_sel_hi:[1,0]
	v_pk_mul_f32 v[28:29], v[44:45], v[0:1] op_sel_hi:[1,0]
	ds_write_b128 v62, v[28:31] offset:16384
	ds_write_b128 v62, v[8:11]
	s_and_saveexec_b64 s[64:65], s[12:13]
	v_mul_f32_e64 v0, v0, -v52
	ds_write_b32 v57, v0 offset:33024
	s_or_b64 exec, exec, s[64:65]
	s_add_i32 s90, s86, 1
	s_cmpk_eq_i32 s86, 0x47
	s_waitcnt lgkmcnt(0)
	s_barrier
	s_cbranch_scc1 .LBB0_131
	v_lshl_add_u32 v0, s90, 5, v53
	s_movk_i32 s2, 0x100
	v_cmp_gt_i32_e32 vcc, s2, v0
	v_add_u32_e32 v1, 0xffffff00, v0
	v_readlane_b32 s2, v255, 30
	v_cndmask_b32_e32 v2, v185, v186, vcc
	v_cndmask_b32_e32 v1, v1, v0, vcc
	v_sub_u32_e32 v0, v2, v0
	v_cndmask_b32_e32 v4, v55, v54, vcc
	v_cndmask_b32_e64 v0, v0, v1, s[22:23]
	v_readlane_b32 s3, v255, 31
	v_add_u32_e32 v2, v0, v4
	v_mov_b32_e32 v49, v3
	v_mov_b64_e32 v[0:1], s[2:3]
	s_movk_i32 s2, 0x600
	v_mad_i64_i32 v[0:1], s[64:65], v2, s2, v[0:1]
	v_lshl_add_u64 v[4:5], v[0:1], 0, s[58:59]
	s_mov_b32 s63, s59
	v_lshl_add_u64 v[4:5], v[4:5], 0, v[48:49]
	v_lshl_add_u64 v[0:1], v[0:1], 0, s[62:63]
	global_load_dwordx2 v[6:7], v[4:5], off
	v_lshl_add_u64 v[0:1], v[0:1], 0, v[48:49]
	v_mov_b64_e32 v[4:5], s[96:97]
	global_load_dwordx2 v[8:9], v[0:1], off offset:1024
	s_nop 0
	global_load_dwordx2 v[10:11], v[0:1], off offset:1280
	v_mad_i64_i32 v[4:5], s[64:65], v2, s76, v[4:5]
	global_load_dword v49, v[4:5], off

; __device__ __forceinline__ float sigmoid_(float x) { return __builtin_amdgcn_rcpf(1.f + __expf(-x)); }
; __device__ __forceinline__ int tid_() { int t = threadIdx.x; asm volatile("" : "+v"(t)); return t; }
; __device__ __forceinline__ void scan_hgrn_mfma(const Params& P, unsigned char* LB, int l, int c) {
;     using CL = ChunkLds<128, 64>;
;     const int tid = tid_(), lane = tid & 63, wave = __builtin_amdgcn_readfirstlane(tid >> 6), fr = lane & 15, fq = lane >> 4;
;     const int vq = c & 1, b = c >> 4, h = (c >> 2) & 3, d = (c >> 1) & 1;
;     const float* U = (const float*)(P.ws + WS_U); bf16* YD = (bf16*)(P.ws + WS_YD);
;     unsigned char* OP = LB;
;     float* tot = (float*)(LB + 58368);
;     const int k = 2 * lane, qt = wave & 3, cb = wave >> 2;
;     const int vv_ = tid & 63, vqt = wave & 3, vc = wave >> 2;
;     f32x2 lb2 = {0.f, 0.f};
;     if (l == 1) { const f32x2 g0 = *(const f32x2*)(P.hgrn_lb_logits + (size_t)(d * 2 + 0) * 512 + h * 128 + k), g1 = *(const f32x2*)(P.hgrn_lb_logits + (size_t)(d * 2 + 1) * 512 + h * 128 + k);
;         lb2.x = sigmoid_(g1.x - g0.x); lb2.y = sigmoid_(g1.y - g0.y); }
;     __syncthreads();
;     zero_operand_pads<128, 64>(OP, tid, 512);
;     f32x4 S[8];
; #pragma unroll
;     for (int i = 0; i < 8; ++i) S[i] = (f32x4){0.f, 0.f, 0.f, 0.f};
;     f32x2 pq[4], pf[4]; float pv[4] = {0.f, 0.f, 0.f, 0.f};
;     ...
;     HGM_LOAD(0);
.LBB0_159:
	s_or_b64 exec, exec, s[6:7]
	s_ashr_i32 s12, s11, 6
	s_and_b32 s21, s12, 3
	s_ashr_i32 s13, s11, 8
	s_ashr_i32 s6, s89, 4
	s_lshl_b32 s7, s13, 4
	s_lshl_b32 s8, s21, 2
	s_or_b32 s38, s8, s7
	s_lshl_b32 s39, s6, 8
	s_lshl_b32 s36, s6, 11
	s_addk_i32 s39, 0x2000
	s_or_b32 s8, s38, 2
	s_add_i32 s6, s38, 0xffffff02
	s_cmpk_lt_i32 s8, 0x100
	s_cselect_b32 s9, 0xff, s33
	s_cselect_b32 s11, s8, s6
	s_cselect_b32 s14, s39, s36
	s_or_b32 s6, s38, 3
	s_add_i32 s7, s38, 0xffffff03
	s_cmpk_lt_i32 s6, 0x100
	s_cselect_b32 s15, 0xff, s33
	s_cselect_b32 s16, s6, s7
	s_cselect_b32 s17, s39, s36
	s_sub_i32 s15, s15, s6
	s_cmp_eq_u32 s20, 0
	s_cselect_b64 s[6:7], -1, 0
	s_and_b64 s[6:7], s[6:7], exec
	s_cselect_b32 s16, s16, s15
	s_sub_i32 s8, s9, s8
	s_cmp_eq_u32 s20, 0
	s_cselect_b64 s[6:7], -1, 0
	s_and_b64 s[6:7], s[6:7], exec
	s_cselect_b32 s15, s11, s8
	s_or_b32 s6, s38, 1
	s_add_i32 s7, s38, 0xffffff01
	s_cmpk_lt_i32 s6, 0x100
	s_cselect_b32 s8, 0xff, s33
	s_cselect_b32 s9, s6, s7
	s_cselect_b32 s11, s39, s36
	s_sub_i32 s8, s8, s6
	s_cmp_eq_u32 s20, 0
	s_cselect_b64 s[6:7], -1, 0
	s_and_b64 s[6:7], s[6:7], exec
	s_cselect_b32 s18, s9, s8
	s_add_i32 s6, s38, 0xffffff00
	s_cmpk_lt_i32 s38, 0x100
	s_cselect_b32 s7, 0xff, s33
	s_cselect_b32 s19, s38, s6
	s_cselect_b32 s23, s39, s36
	s_sub_i32 s22, s7, s38
	s_cmp_eq_u32 s20, 0
	s_cselect_b64 s[6:7], -1, 0
	s_and_b64 s[8:9], s[6:7], exec
	s_cselect_b32 s8, s19, s22
	s_add_i32 s26, s8, s23
	s_lshl_b32 s22, s10, 7
	s_mul_i32 s9, s26, 0x1400
	v_readlane_b32 s42, v255, 35
	s_mul_hi_i32 s8, s26, 0x1400
	v_readlane_b32 s43, v255, 36
	s_add_u32 s24, s42, s9
	s_mul_i32 s23, s26, 0x2a00
	s_addc_u32 s27, s43, s8
	s_mul_hi_i32 s19, s26, 0x2a00
	s_add_u32 s8, s94, s23
	s_addc_u32 s9, s95, s19
	s_lshl_b32 s25, s10, 8
	s_add_u32 s8, s8, s25
	s_addc_u32 s9, s9, 0
	v_lshlrev_b32_e32 v8, 1, v2
	v_mov_b32_e32 v9, v3
	s_lshl_b32 s23, s20, 11
	v_lshl_add_u64 v[10:11], s[8:9], 0, v[8:9]
	s_add_u32 s8, s24, s23
	s_addc_u32 s9, s27, 0
	s_lshl_b32 s24, s10, 9
	s_add_u32 s8, s8, s24
	s_addc_u32 s9, s9, 0
	s_add_i32 s27, s18, s11
	s_mul_i32 s11, s27, 0x1400
	s_mul_hi_i32 s10, s27, 0x1400
	s_add_u32 s28, s42, s11
	s_mul_i32 s19, s27, 0x2a00
	s_addc_u32 s29, s43, s10
	s_mul_hi_i32 s18, s27, 0x2a00
	s_add_u32 s10, s94, s19
	s_addc_u32 s11, s95, s18
	s_add_u32 s10, s10, s25
	s_addc_u32 s11, s11, 0
	v_lshl_add_u64 v[12:13], s[10:11], 0, v[8:9]
	s_add_u32 s10, s28, s23
	s_addc_u32 s11, s29, 0
	s_add_u32 s10, s10, s24
	s_addc_u32 s11, s11, 0
	s_add_i32 s28, s15, s14
	s_mul_i32 s15, s28, 0x1400
	s_mul_hi_i32 s14, s28, 0x1400
	s_add_u32 s29, s42, s15
	s_mul_i32 s19, s28, 0x2a00
	s_addc_u32 s30, s43, s14
	s_mul_hi_i32 s18, s28, 0x2a00
	s_add_u32 s14, s94, s19
	s_addc_u32 s15, s95, s18
	s_add_u32 s14, s14, s25
	s_addc_u32 s15, s15, 0
	v_lshl_add_u64 v[14:15], s[14:15], 0, v[8:9]
	s_add_u32 s14, s29, s23
	s_addc_u32 s15, s30, 0
	s_add_u32 s14, s14, s24
	s_addc_u32 s15, s15, 0
	s_add_i32 s29, s16, s17
	s_mul_i32 s17, s29, 0x1400
	s_mul_hi_i32 s16, s29, 0x1400
	s_add_u32 s18, s42, s17
	s_addc_u32 s19, s43, s16
	s_mul_i32 s17, s29, 0x2a00
	s_mov_b32 s2, 0x26201000
	s_mul_hi_i32 s16, s29, 0x2a00
	s_add_u32 s17, s94, s17
	v_add_co_u32_e32 v10, vcc, s2, v10
	s_addc_u32 s30, s95, s16
	s_nop 0
	v_addc_co_u32_e32 v11, vcc, 0, v11, vcc
	s_add_u32 s16, s17, s25
	v_add_co_u32_e32 v12, vcc, s2, v12
	s_addc_u32 s17, s30, 0
	s_nop 0
	v_addc_co_u32_e32 v13, vcc, 0, v13, vcc
	v_lshl_add_u64 v[8:9], s[16:17], 0, v[8:9]
	s_add_u32 s16, s18, s23
	v_add_co_u32_e32 v14, vcc, s2, v14
	s_addc_u32 s17, s19, 0
	s_nop 0
	v_addc_co_u32_e32 v15, vcc, 0, v15, vcc
	s_add_u32 s16, s16, s24
	v_add_co_u32_e32 v8, vcc, s2, v8
	s_addc_u32 s17, s17, 0
	v_readlane_b32 s2, v255, 45
	s_add_u32 s18, s2, s25
	v_readlane_b32 s2, v255, 46
	s_addc_u32 s19, s2, 0
	s_lshl_b32 s30, s89, 7
	s_and_b32 s31, s30, 0x80
	s_add_u32 s18, s18, s31
	s_addc_u32 s19, s19, 0
	v_addc_co_u32_e32 v9, vcc, 0, v9, vcc
	v_lshl_add_u64 v[56:57], s[18:19], 0, v[2:3]
	global_load_dword v5, v[10:11], off offset:2048
	global_load_dword v16, v[12:13], off offset:2048
	s_nop 0
	global_load_dword v14, v[14:15], off offset:2048
	s_nop 0
	global_load_dword v15, v[8:9], off offset:2048
	v_mad_i64_i32 v[8:9], s[18:19], s26, v190, v[56:57]
	v_mad_i64_i32 v[10:11], s[18:19], s27, v190, v[56:57]
	v_mad_i64_i32 v[12:13], s[18:19], s29, v190, v[56:57]
	global_load_ushort v12, v[12:13], off
	s_nop 0
	global_load_ushort v13, v[8:9], off
	s_nop 0
	global_load_ushort v10, v[10:11], off
	v_mad_i64_i32 v[8:9], s[18:19], s28, v190, v[56:57]
	global_load_ushort v8, v[8:9], off
	s_nop 0
	global_load_dwordx2 v[66:67], v4, s[8:9] offset:64
	global_load_dwordx2 v[64:65], v4, s[10:11] offset:64
	global_load_dwordx2 v[62:63], v4, s[14:15] offset:64
	global_load_dwordx2 v[58:59], v4, s[16:17] offset:64
	s_lshl_b32 s8, s13, 11
	s_add_i32 s8, s8, 0
	s_lshl_b32 s9, s21, 9
	s_mulk_i32 s13, 0x7100
	s_add_i32 s9, s8, s9
	s_add_i32 s37, s13, 0
	s_cmp_lt_u32 s21, 2
	s_cselect_b64 s[26:27], -1, 0
	s_cmp_eq_u32 s21, 0
	s_cselect_b64 s[18:19], -1, 0
	s_cmp_eq_u32 s21, 3
	v_lshrrev_b32_e32 v9, 4, v7
	s_cselect_b64 s[16:17], -1, 0
	s_movk_i32 s2, 0xa0
	s_lshl_b32 s34, s21, 3
	v_and_b32_e32 v116, 15, v6
	s_cmp_lt_i32 s12, 4
	s_waitcnt vmcnt(0)
; __device__ __forceinline__ unsigned cvtpk(float lo, float hi) { f32x2 v = {lo, hi}; bf16x2_n b = __builtin_convertvector(v, bf16x2_n); return __builtin_bit_cast(unsigned, b); }
; __device__ __forceinline__ void scan_hgrn_mfma(const Params& P, unsigned char* LB, int l, int c) {
;     ...
;     f32x4 S[8];
; #pragma unroll
;     for (int i = 0; i < 8; ++i) S[i] = (f32x4){0.f, 0.f, 0.f, 0.f};
;     f32x2 pq[4], pf[4]; float pv[4] = {0.f, 0.f, 0.f, 0.f};
;     ...
;     HGM_LOAD(0);
;     ...
;                 const f32x4 y = chunk_step<128, 64>(OP + ch * CL::SIZE, wave * 16, fr, fq, S);
;                 const int row = scan_row(b, d, tile * 32 + ch * 16 + fr);
;                 { u32x2 w_; w_.x = cvtpk(y[0], y[1]); w_.y = cvtpk(y[2], y[3]); *(u32x2*)(YD + ((size_t)(2 * 2 + d) * MALL + row) * 512 + h * 128 + vq * 64 + wave * 16 + 4 * fq) = w_; }
	v_and_b32_e32 v119, 48, v6
	v_lshlrev_b32_e32 v6, 2, v9
	v_add_u32_e32 v125, s9, v4
	v_add_u32_e32 v124, s8, v4
	s_cselect_b64 s[28:29], -1, 0
	v_lshlrev_b32_e32 v121, 3, v7
	s_lshl_b32 s30, s12, 4
	v_cmp_gt_u32_e64 s[14:15], v6, v116
	v_cmp_lt_u32_e64 s[8:9], v6, v116
	s_mulk_i32 s20, 0x2400
	s_add_i32 s58, s20, 0x9000
	v_lshlrev_b32_e32 v52, 3, v9
	v_mov_b32_e32 v53, v3
	v_mov_b32_e32 v32, 0
	s_mov_b32 s40, 0
	v_pk_add_f32 v[54:55], v[0:1], 1.0 op_sel_hi:[1,0] neg_lo:[1,0] neg_hi:[1,0]
	v_mul_u32_u24_e32 v118, 0x50, v116
	v_add_u32_e32 v117, 0, v119
	v_sub_u32_e32 v126, 0, v116
	v_lshlrev_b32_e32 v2, 1, v2
	s_mov_b32 s44, 0
	v_mov_b32_e32 v33, v32
	v_mov_b32_e32 v34, v32
	v_mov_b32_e32 v35, v32
	v_mov_b32_e32 v28, v32
	v_mov_b32_e32 v29, v32
	v_mov_b32_e32 v30, v32
	v_mov_b32_e32 v31, v32
	v_mov_b32_e32 v24, v32
	v_mov_b32_e32 v25, v32
	v_mov_b32_e32 v26, v32
	v_mov_b32_e32 v27, v32
	v_mov_b32_e32 v20, v32
	v_mov_b32_e32 v21, v32
	v_mov_b32_e32 v22, v32
	v_mov_b32_e32 v23, v32
	v_mov_b32_e32 v17, v32
	v_mov_b32_e32 v18, v32
	v_mov_b32_e32 v19, v32
	v_mov_b32_e32 v9, v32
	s_waitcnt vmcnt(11)
	v_lshlrev_b32_e32 v70, 16, v5
	v_and_b32_e32 v71, 0xffff0000, v5
	v_mov_b32_e32 v5, v3
	s_waitcnt vmcnt(10)
	v_lshlrev_b32_e32 v68, 16, v16
	v_and_b32_e32 v69, 0xffff0000, v16
	s_waitcnt vmcnt(9)
	v_lshlrev_b32_e32 v50, 16, v14
	v_and_b32_e32 v51, 0xffff0000, v14
	s_waitcnt vmcnt(8)
	v_lshlrev_b32_e32 v48, 16, v15
	v_and_b32_e32 v49, 0xffff0000, v15
	s_waitcnt vmcnt(6)
	v_lshlrev_b32_e32 v44, 16, v13
	s_waitcnt vmcnt(5)
	v_lshlrev_b32_e32 v45, 16, v10
	v_lshl_add_u32 v10, v7, 2, s37
	v_lshlrev_b32_e32 v47, 16, v12
	s_waitcnt vmcnt(4)
	v_lshlrev_b32_e32 v46, 16, v8
	v_mov_b32_e32 v8, s37
	v_mad_u32_u24 v11, v7, s2, v8
	s_movk_i32 s2, 0x50
	v_mad_u32_u24 v8, v7, s2, v8
	v_or_b32_e32 v7, 2, v6
	v_or_b32_e32 v6, 3, v6
	v_cmp_gt_u32_e64 s[12:13], v6, v116
	v_or_b32_e32 v6, s30, v116
	v_mul_lo_u32 v6, v6, s2
	v_readlane_b32 s2, v255, 32
	s_add_u32 s20, s2, s25
	v_readlane_b32 s2, v255, 33
	s_addc_u32 s25, s2, 0
	s_add_u32 s20, s20, s31
	s_addc_u32 s25, s25, 0
	s_ashr_i32 s31, s30, 31
	s_lshl_b64 s[30:31], s[30:31], 1
	s_add_u32 s30, s20, s30
	s_addc_u32 s31, s25, s31
	s_add_u32 s20, s42, s23
	s_mul_i32 s25, s21, 0x440
	s_addc_u32 s21, s43, 0
	s_add_u32 s20, s20, s24
	s_movk_i32 s2, 0x110
	s_addc_u32 s21, s21, 0
	v_cmp_gt_u32_e64 s[10:11], v7, v116
	v_lshl_add_u64 v[76:77], s[30:31], 0, v[52:53]
	v_mad_u32_u24 v53, v116, s2, 0
	v_add_u32_e32 v120, 0, v6
	v_lshl_add_u64 v[60:61], s[20:21], 0, v[4:5]
	s_sub_i32 s41, 0, s38
	s_lshl_b32 s42, s22, 1
	v_add_u32_e32 v123, s25, v10
	v_add_u32_e32 v127, s34, v11
	v_add_u32_e32 v122, s34, v8
	s_mov_b32 s43, 0
	v_mov_b32_e32 v16, v32
	v_mov_b32_e32 v12, v32
	v_mov_b32_e32 v13, v32
	v_mov_b32_e32 v14, v32
	v_mov_b32_e32 v15, v32
	v_mov_b32_e32 v8, v32
	v_mov_b32_e32 v10, v32
	v_mov_b32_e32 v11, v32
	v_mov_b32_e32 v4, v32
	v_mov_b32_e32 v5, v32
	v_mov_b32_e32 v6, v32
	v_mov_b32_e32 v7, v32
	s_waitcnt vmcnt(0)
	s_branch .LBB0_162
.LBB0_160:
	s_nop 4
	v_pk_add_f32 v[38:39], v[38:39], v[42:43]
	v_pk_add_f32 v[36:37], v[36:37], v[40:41]
	v_ashrrev_i32_e32 v45, 31, v44
	v_cvt_pk_bf16_f32 v36, v36, v37
	v_cvt_pk_bf16_f32 v37, v38, v39
	v_lshl_add_u64 v[38:39], v[44:45], 0, s[58:59]
	v_lshlrev_b64 v[38:39], 10, v[38:39]
	v_lshl_add_u64 v[38:39], v[76:77], 0, v[38:39]
	global_store_dwordx2 v[38:39], v[36:37], off
	s_waitcnt vmcnt(2)
	s_branch .Lhg_unpack

; __device__ __forceinline__ void scan_hgrn_mfma(const Params& P, unsigned char* LB, int l, int c) {
;     ...
;     for (int tile = 0; tile < NTILES; ++tile) {
;         f32x2 q[4], kk[4], pre[4], suf[4]; float vv[4];
;         { f32x2 fc[4];
; #pragma unroll
;           for (int r = 0; r < 4; ++r) {
;               const float eq0 = 1.f + __expf(fminf(-pq[r].x, 40.f)), ef0 = 1.f + __expf(fminf(-pf[r].x, 40.f)), r0_ = __builtin_amdgcn_rcpf(eq0 * ef0);
;               const float eq1 = 1.f + __expf(fminf(-pq[r].y, 40.f)), ef1 = 1.f + __expf(fminf(-pf[r].y, 40.f)), r1_ = __builtin_amdgcn_rcpf(eq1 * ef1);
;               q[r].x = pq[r].x * (ef0 * r0_) * 0.08838834764831845f; q[r].y = pq[r].y * (ef1 * r1_) * 0.08838834764831845f;
;               const float f0 = lb2.x + (1.f - lb2.x) * (eq0 * r0_), f1 = lb2.y + (1.f - lb2.y) * (eq1 * r1_);
;               kk[r].x = 1.f - f0; kk[r].y = 1.f - f1; fc[r].x = fmaxf(f0, 1e-4f); fc[r].y = fmaxf(f1, 1e-4f); vv[r] = pv[r];
;           }
;           pre[0] = fc[0]; pre[1] = pre[0] * fc[1]; pre[2] = pre[1] * fc[2]; pre[3] = pre[2] * fc[3];
;           suf[3] = (f32x2){1.f, 1.f}; suf[2] = fc[3]; suf[1] = suf[2] * fc[2]; suf[0] = suf[1] * fc[1]; }
;         *(f32x2*)&tot[(cb * 4 + qt) * 128 + k] = pre[3];
;         __syncthreads();
;         if (tile + 1 < NTILES) HGM_LOAD(tile + 1);
.Lhg_unpack:
	s_add_i32 s43, s43, 32
	s_sub_i32 s40, s40, 32
	s_add_i32 s44, s44, 1
	v_lshlrev_b32_e32 v70, 16, v128
	v_and_b32_e32 v71, 0xffff0000, v128
	v_lshlrev_b32_e32 v68, 16, v129
	v_and_b32_e32 v69, 0xffff0000, v129
	v_lshlrev_b32_e32 v50, 16, v131
	v_and_b32_e32 v51, 0xffff0000, v131
	v_lshlrev_b32_e32 v48, 16, v132
	v_and_b32_e32 v49, 0xffff0000, v132
	v_lshlrev_b32_e32 v45, 16, v137
	v_lshlrev_b32_e32 v44, 16, v136
	v_lshlrev_b32_e32 v47, 16, v135
	s_cmpk_eq_i32 s43, 0x8e0
	v_lshlrev_b32_e32 v46, 16, v130
	s_cbranch_scc1 .LBB0_189
.LBB0_162:
	v_max_f32_e64 v37, -v66, -v66
	v_min_f32_e32 v37, 0x42200000, v37
	v_mul_f32_e32 v37, 0x3fb8aa3b, v37
	v_max_f32_e64 v36, -v70, -v70
	v_exp_f32_e32 v38, v37
	v_max_f32_e64 v37, -v71, -v71
	v_max_f32_e64 v39, -v67, -v67
	v_min_f32_e32 v36, 0x42200000, v36
	v_min_f32_e32 v37, 0x42200000, v37
	v_min_f32_e32 v39, 0x42200000, v39
	v_mul_f32_e32 v36, 0x3fb8aa3b, v36
	v_mul_f32_e32 v37, 0x3fb8aa3b, v37
	v_mul_f32_e32 v39, 0x3fb8aa3b, v39
	v_exp_f32_e32 v36, v36
	v_exp_f32_e32 v39, v39
	v_exp_f32_e32 v37, v37
	v_max_f32_e64 v41, -v65, -v65
	v_min_f32_e32 v41, 0x42200000, v41
	v_pk_add_f32 v[94:95], v[38:39], 1.0 op_sel_hi:[1,0]
	v_pk_add_f32 v[36:37], v[36:37], 1.0 op_sel_hi:[1,0]
	v_mul_f32_e32 v41, 0x3fb8aa3b, v41
	v_pk_mul_f32 v[38:39], v[36:37], v[94:95]
	v_exp_f32_e32 v41, v41
	v_rcp_f32_e32 v99, v39
	v_max_f32_e64 v39, -v64, -v64
	v_min_f32_e32 v39, 0x42200000, v39
	v_mul_f32_e32 v39, 0x3fb8aa3b, v39
	v_rcp_f32_e32 v98, v38
	v_max_f32_e64 v38, -v68, -v68
	v_exp_f32_e32 v40, v39
	v_max_f32_e64 v39, -v69, -v69
	v_min_f32_e32 v38, 0x42200000, v38
	v_min_f32_e32 v39, 0x42200000, v39
	v_mul_f32_e32 v38, 0x3fb8aa3b, v38
	v_mul_f32_e32 v39, 0x3fb8aa3b, v39
	v_exp_f32_e32 v38, v38
	v_exp_f32_e32 v39, v39
	v_pk_add_f32 v[86:87], v[40:41], 1.0 op_sel_hi:[1,0]
	v_pk_mul_f32 v[36:37], v[36:37], v[98:99]
	s_add_i32 s22, s38, s43
	v_pk_add_f32 v[38:39], v[38:39], 1.0 op_sel_hi:[1,0]
	v_pk_fma_f32 v[102:103], v[54:55], v[36:37], v[0:1]
	v_pk_mul_f32 v[40:41], v[38:39], v[86:87]
	s_add_i32 s20, s22, 32
	v_rcp_f32_e32 v88, v40
	v_rcp_f32_e32 v89, v41
	v_max_f32_e64 v41, -v63, -v63
	v_min_f32_e32 v41, 0x42200000, v41
	v_mul_f32_e32 v41, 0x3fb8aa3b, v41
	v_pk_mul_f32 v[36:37], v[38:39], v[88:89]
	v_max_f32_e64 v39, -v62, -v62
	v_min_f32_e32 v39, 0x42200000, v39
	v_mul_f32_e32 v39, 0x3fb8aa3b, v39
	v_max_f32_e64 v38, -v50, -v50
	v_exp_f32_e32 v40, v39
	v_max_f32_e64 v39, -v51, -v51
	v_min_f32_e32 v38, 0x42200000, v38
	v_min_f32_e32 v39, 0x42200000, v39
	v_mul_f32_e32 v38, 0x3fb8aa3b, v38
	v_mul_f32_e32 v39, 0x3fb8aa3b, v39
	v_exp_f32_e32 v38, v38
	v_exp_f32_e32 v41, v41
	v_exp_f32_e32 v39, v39
	v_pk_fma_f32 v[92:93], v[54:55], v[36:37], v[0:1]
	s_add_i32 s21, s22, 0xffffff20
	v_pk_add_f32 v[80:81], v[40:41], 1.0 op_sel_hi:[1,0]
	v_pk_add_f32 v[36:37], v[38:39], 1.0 op_sel_hi:[1,0]
	v_max_f32_e64 v41, -v59, -v59
	v_pk_mul_f32 v[38:39], v[36:37], v[80:81]
	v_min_f32_e32 v41, 0x42200000, v41
	v_rcp_f32_e32 v85, v39
	v_max_f32_e64 v39, -v58, -v58
	v_min_f32_e32 v39, 0x42200000, v39
	v_mul_f32_e32 v39, 0x3fb8aa3b, v39
	v_rcp_f32_e32 v84, v38
	v_max_f32_e64 v38, -v48, -v48
	v_exp_f32_e32 v40, v39
	v_max_f32_e64 v39, -v49, -v49
	v_min_f32_e32 v38, 0x42200000, v38
	v_min_f32_e32 v39, 0x42200000, v39
	s_cmpk_lt_i32 s20, 0x100
	v_mul_f32_e32 v38, 0x3fb8aa3b, v38
	v_mul_f32_e32 v39, 0x3fb8aa3b, v39
	v_mul_f32_e32 v41, 0x3fb8aa3b, v41
	s_cselect_b32 s23, 0xff, s33
	v_exp_f32_e32 v38, v38
	v_exp_f32_e32 v41, v41
	v_exp_f32_e32 v39, v39
	s_cselect_b32 s24, s20, s21
	s_cselect_b32 s25, s39, s36
	s_add_i32 s20, s41, s23
	s_add_i32 s20, s20, s40
	s_sub_i32 s23, s20, 32
	s_and_b64 s[20:21], s[6:7], exec
	v_pk_add_f32 v[72:73], v[40:41], 1.0 op_sel_hi:[1,0]
	v_pk_add_f32 v[38:39], v[38:39], 1.0 op_sel_hi:[1,0]
	s_cselect_b32 s20, s24, s23
	v_pk_mul_f32 v[40:41], v[38:39], v[72:73]
	s_add_i32 s23, s20, s25
	v_rcp_f32_e32 v74, v40
	v_rcp_f32_e32 v75, v41
	s_mul_i32 s21, s23, 0x2a00
	s_mul_hi_i32 s20, s23, 0x2a00
	s_add_u32 s21, s94, s21
	s_addc_u32 s24, s95, s20
	s_add_u32 s20, s21, s42
	v_pk_mul_f32 v[38:39], v[38:39], v[74:75]
	s_addc_u32 s21, s24, 0
	v_pk_fma_f32 v[78:79], v[54:55], v[38:39], v[0:1]
	v_lshl_add_u64 v[38:39], s[20:21], 0, v[2:3]
	v_mad_i64_i32 v[40:41], s[20:21], s23, v191, v[60:61]
	s_add_i32 s20, s22, 33
	s_add_i32 s21, s22, 0xffffff21
	s_cmpk_lt_i32 s20, 0x100
	s_cselect_b32 s24, 0xff, s33
	s_cselect_b32 s25, s20, s21
	s_cselect_b32 s30, s39, s36
	s_add_i32 s20, s41, s24
	s_add_i32 s20, s20, s40
	s_sub_i32 s24, s20, 33
	s_and_b64 s[20:21], s[6:7], exec
	s_cselect_b32 s20, s25, s24
	s_add_i32 s24, s20, s30
	s_mul_i32 s21, s24, 0x2a00
	s_mul_hi_i32 s20, s24, 0x2a00
	s_add_u32 s21, s94, s21
	s_addc_u32 s25, s95, s20
	s_add_u32 s20, s21, s42
	s_addc_u32 s21, s25, 0
	v_lshl_add_u64 v[42:43], s[20:21], 0, v[2:3]
	v_mad_i64_i32 v[58:59], s[20:21], s24, v191, v[60:61]
	s_add_i32 s20, s22, 34
	s_add_i32 s21, s22, 0xffffff22
	s_cmpk_lt_i32 s20, 0x100
	s_cselect_b32 s25, 0xff, s33
	s_cselect_b32 s30, s20, s21
	s_cselect_b32 s31, s39, s36
	s_add_i32 s20, s41, s25
	s_add_i32 s20, s20, s40
	s_sub_i32 s25, s20, 34
	s_and_b64 s[20:21], s[6:7], exec
	s_cselect_b32 s20, s30, s25
	s_add_i32 s25, s20, s31
	v_pk_mul_f32 v[36:37], v[36:37], v[84:85]
	s_mul_i32 s21, s25, 0x2a00
	v_max_f32_e32 v106, 0x38d1b717, v102
	v_max_f32_e32 v107, 0x38d1b717, v103
	v_max_f32_e32 v110, 0x38d1b717, v92
	v_max_f32_e32 v111, 0x38d1b717, v93
	v_pk_fma_f32 v[90:91], v[54:55], v[36:37], v[0:1]
	s_mov_b32 s2, 0x26201000
	s_mul_hi_i32 s20, s25, 0x2a00
	s_add_u32 s21, s94, s21
	v_max_f32_e32 v36, 0x38d1b717, v90
	v_max_f32_e32 v37, 0x38d1b717, v91
	v_pk_mul_f32 v[108:109], v[110:111], v[106:107]
	v_add_co_u32_e32 v38, vcc, s2, v38
	s_addc_u32 s30, s95, s20
	v_max_f32_e32 v100, 0x38d1b717, v78
	v_max_f32_e32 v101, 0x38d1b717, v79
	v_pk_mul_f32 v[96:97], v[36:37], v[108:109]
	v_addc_co_u32_e32 v39, vcc, 0, v39, vcc
	s_add_u32 s20, s21, s42
	v_pk_mul_f32 v[82:83], v[100:101], v[96:97]
	v_add_co_u32_e32 v42, vcc, s2, v42
	s_addc_u32 s21, s30, 0
	ds_write_b64 v125, v[82:83] offset:58368
	s_waitcnt lgkmcnt(0)
	s_barrier
; __device__ __forceinline__ void scan_hgrn_mfma(const Params& P, unsigned char* LB, int l, int c) {
;     ...
;         if (tile + 1 < NTILES) HGM_LOAD(tile + 1);
;         {
;             const f32x2 t0 = *(const f32x2*)&tot[(cb * 4 + 0) * 128 + k], t1 = *(const f32x2*)&tot[(cb * 4 + 1) * 128 + k], t2 = *(const f32x2*)&tot[(cb * 4 + 2) * 128 + k], t3 = *(const f32x2*)&tot[(cb * 4 + 3) * 128 + k];
;             const f32x2 Pm = t0 * t1, T23 = t2 * t3;
;             unsigned char* C = OP + cb * CL::SIZE;
;             float kw0[4], kw1[4];
; #pragma unroll
;             for (int r = 0; r < 4; ++r) {
;                 const int t = qt * 4 + r;
;                 f32x2 R, iR;
;                 if (qt >= 2) { R = pre[r]; if (qt == 3) R *= t2; iR.x = __builtin_amdgcn_rcpf(R.x); iR.y = __builtin_amdgcn_rcpf(R.y); }
;                 else { iR = suf[r]; if (qt == 0) iR *= t1; R.x = __builtin_amdgcn_rcpf(iR.x); R.y = __builtin_amdgcn_rcpf(iR.y); }
	v_addc_co_u32_e32 v43, vcc, 0, v43, vcc
	global_load_dword v128, v[38:39], off offset:2048
	global_load_dwordx2 v[66:67], v[40:41], off offset:64
	global_load_dword v129, v[42:43], off offset:2048
	global_load_dwordx2 v[64:65], v[58:59], off offset:64
	v_lshl_add_u64 v[38:39], s[20:21], 0, v[2:3]
	v_mad_i64_i32 v[40:41], s[20:21], s25, v191, v[60:61]
	s_add_i32 s20, s22, 35
	s_addk_i32 s22, 0xff23
	s_cmpk_lt_i32 s20, 0x100
	s_cselect_b32 s21, 0xff, s33
	s_cselect_b32 s22, s20, s22
	s_cselect_b32 s30, s39, s36
	s_add_i32 s20, s41, s21
	s_add_i32 s20, s20, s40
	s_sub_i32 s31, s20, 35
	s_and_b64 s[20:21], s[6:7], exec
	s_cselect_b32 s20, s22, s31
	s_add_i32 s22, s20, s30
	s_mul_i32 s21, s22, 0x2a00
	s_mul_hi_i32 s20, s22, 0x2a00
	s_add_u32 s21, s94, s21
	s_addc_u32 s30, s95, s20
	s_add_u32 s20, s21, s42
	v_add_co_u32_e32 v38, vcc, s2, v38
	s_addc_u32 s21, s30, 0
	s_nop 0
	v_addc_co_u32_e32 v39, vcc, 0, v39, vcc
	v_lshl_add_u64 v[42:43], s[20:21], 0, v[2:3]
	v_add_co_u32_e32 v42, vcc, s2, v42
	v_mad_i64_i32 v[58:59], s[20:21], s22, v191, v[60:61]
	s_nop 0
	v_addc_co_u32_e32 v43, vcc, 0, v43, vcc
	global_load_dword v131, v[38:39], off offset:2048
	global_load_dwordx2 v[62:63], v[40:41], off offset:64
	global_load_dword v132, v[42:43], off offset:2048
	s_nop 0
	global_load_dwordx2 v[58:59], v[58:59], off offset:64
	v_mad_i64_i32 v[38:39], s[20:21], s23, v190, v[56:57]
	v_mad_i64_i32 v[40:41], s[20:21], s24, v190, v[56:57]
	v_mad_i64_i32 v[42:43], s[20:21], s25, v190, v[56:57]
	v_mad_i64_i32 v[104:105], s[20:21], s22, v190, v[56:57]
	global_load_ushort v136, v[38:39], off
	global_load_ushort v137, v[40:41], off
	global_load_ushort v130, v[42:43], off
	global_load_ushort v135, v[104:105], off
	v_pk_mul_f32 v[112:113], v[100:101], v[36:37]
	ds_read2st64_b64 v[40:43], v124 offset0:114 offset1:115
	ds_read2st64_b64 v[36:39], v124 offset0:116 offset1:117
	s_mov_b64 s[20:21], -1
	s_and_b64 vcc, exec, s[26:27]
	s_cbranch_vccz .LBB0_164
	v_pk_mul_f32 v[104:105], v[110:111], v[112:113]
	s_mov_b64 s[20:21], 0
	s_waitcnt lgkmcnt(1)
	v_pk_mul_f32 v[110:111], v[104:105], v[42:43]
	s_nop 0
	v_cndmask_b32_e64 v105, v105, v111, s[18:19]
	v_cndmask_b32_e64 v104, v104, v110, s[18:19]
	v_rcp_f32_e32 v114, v104
	v_rcp_f32_e32 v115, v105

; __device__ __forceinline__ int bid_() { int t = blockIdx.x; asm volatile("" : "+s"(t)); return t; }
; __device__ __forceinline__ void prologue_phase(const Params& P, float* L) {
;     ...
;     bf16* W13 = (bf16*)(ws + WS_W13); bf16* W2 = (bf16*)(ws + WS_W2); bf16* WIN = (bf16*)(ws + WS_WIN); bf16* WOUT = (bf16*)(ws + WS_WOUT);
;     float* scr = L + wave * (64 * 65);
;     const int gw = bid_() * 8 + wave, NGW = gridDim.x * 8;
;     constexpr int I_F = 2816, I_LF = 3 * I_F, I_FFN = 4 * I_LF, I_IN = 32 * 101, I_OUT = 32 * 32, I_ALL = I_FFN + 2 * I_IN + 2 * I_OUT;
;     for (int it = gw; it < I_ALL; it += NGW) {
.LBB0_379:
	s_lshl_b32 s18, s2, 3
	v_readfirstlane_b32 s0, v168
	s_lshr_b32 s0, s0, 6
	s_add_u32 s18, s18, s0
	s_load_dword s20, s[38:39], 0x0
	s_mov_b32 s19, 5632
	s_mov_b32 s98, 5632
	s_mov_b32 s99, 0
	s_mov_b32 s100, 0xffffea00
	s_waitcnt lgkmcnt(0)
	s_lshl_b32 s20, s20, 3

; __device__ __forceinline__ int bid_() { int t = blockIdx.x; asm volatile("" : "+s"(t)); return t; }
; __device__ __forceinline__ void prologue_phase(const Params& P, float* L) {
;     ...
;     bf16* W13 = (bf16*)(ws + WS_W13); bf16* W2 = (bf16*)(ws + WS_W2); bf16* WIN = (bf16*)(ws + WS_WIN); bf16* WOUT = (bf16*)(ws + WS_WOUT);
;     float* scr = L + wave * (64 * 65);
;     const int gw = bid_() * 8 + wave, NGW = gridDim.x * 8;
;     constexpr int I_F = 2816, I_LF = 3 * I_F, I_FFN = 4 * I_LF, I_IN = 32 * 101, I_OUT = 32 * 32, I_ALL = I_FFN + 2 * I_IN + 2 * I_OUT;
;     for (int it = gw; it < I_ALL; it += NGW) {
;         int r = it;
;         if (r < I_FFN) {
;             const int lf = r / I_LF, q = r % I_LF, which = q / I_F, item = q % I_F;
;             if (which == 0) transpose_item64(P.ffn_w1 + (size_t)lf * DM * FF, DM, FF, W13 + (size_t)lf * NUP * DM, 1, scr, item, lane);
;             else if (which == 1) transpose_item64(P.ffn_w3 + (size_t)lf * DM * FF, DM, FF, W13 + (size_t)lf * NUP * DM, 2, scr, item, lane);
;             else transpose_item64(P.ffn_w2 + (size_t)lf * FF * DM, FF, DM, W2 + (size_t)lf * DM * FF, 0, scr, item, lane);
;         } else {
;             r -= I_FFN;
;             if (r < 2 * I_IN) { const int l = r / I_IN, item = r % I_IN; transpose_item64(P.w_in + (size_t)l * DM * NIN, DM, NIN, WIN + (size_t)l * NINP_W * DM, 3, scr, item, lane); }
;             else { r -= 2 * I_IN; const int l = r / I_OUT, item = r % I_OUT; transpose_item64(P.w_out + (size_t)l * DM * DM, DM, DM, WOUT + (size_t)l * DM * DM, 0, scr, item, lane); }
;         }
;     }
.LBB0_571:
	s_cmp_eq_u32 s36, 2
	s_cbranch_scc0 .Lhk_n0
	s_cmp_ge_u32 s2, 48
	s_cbranch_scc0 .Lhk_n0
	s_cmp_lt_u32 s2, 256
	s_cbranch_scc0 .Lhk_n0
	s_mov_b32 s0, 48
	s_mov_b32 s1, 208
	s_mov_b32 s99, 5632
	s_mov_b32 s98, 2816
	s_mov_b32 s100, 0x7900
	s_mov_b32 s19, 6048
	s_branch .Lhk_go
.Lhk_n0:
	s_cmp_eq_u32 s36, 5
	s_cbranch_scc0 .Lhk_n1
	s_cmp_ge_u32 s2, 168
	s_cbranch_scc0 .Lhk_n1
	s_cmp_lt_u32 s2, 256
	s_cbranch_scc0 .Lhk_n1
	s_mov_b32 s0, 168
	s_mov_b32 s1, 88
	s_mov_b32 s99, 40256
	s_mov_b32 s98, 1024
	s_mov_b32 s100, 0x1d00
	s_mov_b32 s19, 6024
	s_branch .Lhk_go
.Lhk_n1:
	s_cmp_eq_u32 s36, 7
	s_cbranch_scc0 .Lhk_n2
	s_cmp_ge_u32 s2, 192
	s_cbranch_scc0 .Lhk_n2
	s_cmp_lt_u32 s2, 256
	s_cbranch_scc0 .Lhk_n2
	s_mov_b32 s0, 192
	s_mov_b32 s1, 64
	s_mov_b32 s99, 13448
	s_mov_b32 s98, 11896
	s_mov_b32 s100, 0xffffd188
	s_mov_b32 s19, 11896
	s_branch .Lhk_go
.Lhk_n2:
	s_cmp_eq_u32 s36, 11
	s_cbranch_scc0 .Lhk_n3
	s_cmp_ge_u32 s2, 48
	s_cbranch_scc0 .Lhk_n3
	s_cmp_lt_u32 s2, 256
	s_cbranch_scc0 .Lhk_n3
	s_mov_b32 s0, 48
	s_mov_b32 s1, 208
	s_mov_b32 s99, 37024
	s_mov_b32 s98, 3232
	s_mov_b32 s100, 0x94a0
	s_mov_b32 s19, 4256
	s_branch .Lhk_go
.Lhk_n3:
	s_cmp_eq_u32 s36, 14
	s_cbranch_scc0 .Lhk_n4
	s_cmp_ge_u32 s2, 48
	s_cbranch_scc0 .Lhk_n4
	s_cmp_lt_u32 s2, 256
	s_cbranch_scc0 .Lhk_n4
	s_mov_b32 s0, 48
	s_mov_b32 s1, 208
	s_mov_b32 s99, 25344
	s_mov_b32 s98, 8448
	s_mov_b32 s100, 0xffffdf00
	s_mov_b32 s19, 8448
	s_branch .Lhk_go

; #define LAS __attribute__((address_space(3)))
; __device__ __forceinline__ unsigned xb_add(unsigned* p, unsigned v) { return __hip_atomic_fetch_add(p, v, __ATOMIC_RELAXED, __HIP_MEMORY_SCOPE_AGENT); }
; __device__ __forceinline__ unsigned xb_xcc_id() { return (unsigned)__builtin_amdgcn_s_getreg((3 << 11) | 20) & 0xFu; }
; __device__ __forceinline__ void xcd_barrier(const XcdBarrier& b) {
;     asm volatile("s_waitcnt vmcnt(0)" ::: "memory");
;     __syncthreads();
;     if (threadIdx.x == 0) {
;         unsigned* bar = b.bar;
;         __builtin_amdgcn_s_waitcnt(0);
;         unsigned nloc = b.st[0], nx = b.st[1];
;         if (nloc == 0u) { xcd_barrier_complete(bar, b.x, nloc, nx); b.st[0] = nloc; b.st[1] = nx; }
;         const unsigned old = xb_add(&bar[XB_XSUB(b.x)], 1u);
; __global__ void __launch_bounds__(512, 2) mk_fwd(Params Pkarg) {
;     ...
;         if (ph + 1 < ph_hi) {
;             if (ph == 0) cg::this_grid().sync();
;             else { XcdBarrier xb; xb.bar = (unsigned*)ws; xb.x = xb_xcc_id(); xb.st = (volatile LAS unsigned*)((LAS unsigned char*)lds_raw + (LDS_BYTES - 128)); xcd_barrier(xb); }
;         }
.Lhk_go:
	s_barrier
	s_sub_u32 s18, s2, s0
	s_lshl_b32 s18, s18, 3
	v_readfirstlane_b32 s21, v168
	s_lshr_b32 s21, s21, 6
	s_add_u32 s18, s18, s21
	s_lshl_b32 s20, s1, 3
	s_branch .Ltr_entry
.Lhk_resume:
	s_add_i32 s36, s36, 1
	s_cmp_ge_i32 s36, s37
	s_mov_b64 s[0:1], -1
	s_cbranch_scc1 .LBB0_10
	v_readlane_b32 s0, v254, 52
	v_readlane_b32 s1, v254, 53
	s_and_b64 vcc, exec, s[0:1]
	s_getreg_b32 s4, hwreg(HW_REG_XCC_ID, 0, 4)
	s_waitcnt vmcnt(0)
	s_waitcnt vmcnt(0)
	s_barrier
	s_mov_b64 s[0:1], exec
	v_readlane_b32 s6, v254, 0
	v_readlane_b32 s7, v254, 1
	s_and_b64 s[6:7], s[0:1], s[6:7]
	s_mov_b64 exec, s[6:7]
	s_cbranch_execz .LBB0_626
	v_readlane_b32 s3, v254, 14
	s_waitcnt vmcnt(0) expcnt(0) lgkmcnt(0)
	s_and_b32 s18, s4, 15
	v_mov_b32_e32 v0, s3
	ds_read_b32 v2, v0
	v_readlane_b32 s3, v254, 15
	s_waitcnt lgkmcnt(0)
	v_cmp_ne_u32_e32 vcc, 0, v2
	v_mov_b32_e32 v0, s3
	ds_read_b32 v0, v0
	s_cbranch_vccnz .LBB0_590
	s_load_dwordx2 s[8:9], s[38:39], 0x0
	s_load_dword s7, s[38:39], 0x8
	s_add_u32 s4, s94, 0x1000
	s_addc_u32 s5, s95, 0
	s_add_u32 s6, s94, 0x1100
	s_waitcnt lgkmcnt(0)
	s_mul_i32 s19, s9, s8
	s_mul_i32 s19, s19, s7
	s_addc_u32 s7, s95, 0
	s_add_u32 s8, s94, 0x1200
	s_addc_u32 s9, s95, 0
	s_add_u32 s10, s94, 0x1300
	s_addc_u32 s11, s95, 0
	s_mov_b32 s20, 1
	s_branch .LBB0_577
